# v46 + P0 weight conversion: per tile the 16 serial ds_read2->wait->cvt LDS round trips become 8-deep pipelined reads with counted lgkmcnt waits (18 blocks)
# baseline (speedup 1.0000x reference)
; __device__ __forceinline__ unsigned cvt_pk_bf16(float lo, float hi) { unsigned r; asm volatile("v_cvt_pk_bf16_f32 %0, %1, %2" : "=v"(r) : "v"(lo), "v"(hi)); return r; }
; __device__ __forceinline__ void cvt_matrix(const float* __restrict__ src, int K, int N, bf16_t* __restrict__ dst, int kind, int& base, float* lds_f, const int wv) {
;     ...
;         const int kt = t / nnb, nb = t % nnb, k0 = kt * 256, n0 = nb * 64;
;         int drow0 = n0, perm = 0;
;         if (kind == 1) { if (n0 < DFF) drow0 = 256 * (n0 >> 7) + (n0 & 127); else { const int n1 = n0 - DFF; drow0 = 256 * (n1 >> 7) + 128 + (n1 & 127); } }
;         if (kind == 2) perm = (n0 % 192) == 128;
;         { const int c4 = tid & 15, kr = tid >> 4;
;           f32x4 v[8];
; #pragma unroll
;           for (int i = 0; i < 8; ++i) v[i] = __builtin_nontemporal_load((const f32x4*)(src + (size_t)(k0 + kr + 32 * i) * N + n0 + 4 * c4));
; #pragma unroll
;           for (int i = 0; i < 8; ++i) { float* l = lds_f + (kr + 32 * i) * 65 + 4 * c4; l[0] = v[i][0]; l[1] = v[i][1]; l[2] = v[i][2]; l[3] = v[i][3]; } }
;         __syncthreads();
; #pragma unroll
;         for (int j = 0; j < 4; ++j) { const int idx = tid + 512 * j, r = ((idx >> 6) & 3) * 16 + ((idx >> 2) & 15), kc = (idx >> 8) * 4 + (idx & 3);
;             const int sc = perm ? ((r & 1) ? 32 + (r >> 1) : (r >> 1)) : r;
;             const float* l = lds_f + (kc * 8) * 65 + sc;
;             u32x4 w; w.x = cvt_pk_bf16(l[0], l[65]); w.y = cvt_pk_bf16(l[2 * 65], l[3 * 65]); w.z = cvt_pk_bf16(l[4 * 65], l[5 * 65]); w.w = cvt_pk_bf16(l[6 * 65], l[7 * 65]);
;             *(u32x4*)(dst + (size_t)(drow0 + r) * K + k0 + kc * 8) = w; }
;         __syncthreads();
.LBB0_48:
	s_cmpk_gt_u32 s85, 0x57f
	s_cbranch_scc1 .LBB0_47
	s_and_b32 s2, s85, 0xffff
	s_mul_i32 s2, s2, 0xba2f
	s_lshr_b32 s26, s2, 23
	s_mulk_i32 s26, 0xb0
	s_sub_i32 s26, s85, s26
	s_and_b32 s26, s26, 0xffff
	s_lshl_b32 s88, s26, 7
	s_lshr_b32 s2, s2, 15
	s_or_b32 s89, s88, 0x80
	s_and_b32 s2, s2, 0xff00
	s_lshl_b32 s87, s26, 6
	s_addk_i32 s89, 0xd400
	s_and_b32 s88, s88, 0x3f00
	s_cmpk_lt_u32 s26, 0x58
	s_cselect_b32 s90, s88, s89
	v_add_u32_e32 v6, s2, v18
	s_lshl_b32 s26, s26, 8
	v_lshl_add_u64 v[76:77], v[8:9], 0, s[26:27]
	v_add_u32_e32 v43, 32, v6
	v_mad_i64_i32 v[52:53], s[88:89], v43, s79, v[76:77]
	v_add_u32_e32 v43, 64, v6
	v_mad_i64_i32 v[56:57], s[88:89], v43, s79, v[76:77]
	v_add_u32_e32 v43, 0x60, v6
	v_mad_i64_i32 v[60:61], s[88:89], v43, s79, v[76:77]
	v_add_u32_e32 v43, 0x80, v6
	v_mad_i64_i32 v[64:65], s[88:89], v43, s79, v[76:77]
	v_add_u32_e32 v43, 0xa0, v6
	v_mad_i64_i32 v[48:49], s[88:89], v6, s79, v[76:77]
	v_mad_i64_i32 v[68:69], s[88:89], v43, s79, v[76:77]
	global_load_dwordx4 v[48:51], v[48:49], off nt
	s_nop 0
	global_load_dwordx4 v[52:55], v[52:53], off nt
	s_nop 0
	global_load_dwordx4 v[56:59], v[56:57], off nt
	s_nop 0
	global_load_dwordx4 v[60:63], v[60:61], off nt
	s_nop 0
	global_load_dwordx4 v[64:67], v[64:65], off nt
	s_nop 0
	global_load_dwordx4 v[68:71], v[68:69], off nt
	v_add_u32_e32 v43, 0xc0, v6
	v_mad_i64_i32 v[72:73], s[88:89], v43, s79, v[76:77]
	global_load_dwordx4 v[72:75], v[72:73], off nt
	v_add_u32_e32 v6, 0xe0, v6
	v_mad_i64_i32 v[76:77], s[88:89], v6, s79, v[76:77]
	global_load_dwordx4 v[76:79], v[76:77], off nt
	s_and_b32 s26, s87, 64
	s_or_b32 s87, s26, s90
	v_or_b32_e32 v6, s87, v19
	s_lshl_b32 s26, s2, 1
	s_waitcnt vmcnt(7)
	ds_write2_b32 v24, v48, v49 offset1:1
	ds_write2_b32 v24, v50, v51 offset0:2 offset1:3
	s_waitcnt vmcnt(6)
	ds_write2_b32 v25, v52, v53 offset1:1
	ds_write2_b32 v26, v54, v55 offset1:1
	s_waitcnt vmcnt(5)
	ds_write2_b32 v27, v56, v57 offset1:1
	ds_write2_b32 v28, v58, v59 offset1:1
	s_waitcnt vmcnt(4)
	ds_write2_b32 v29, v60, v61 offset1:1
	ds_write2_b32 v30, v62, v63 offset1:1
	s_waitcnt vmcnt(3)
	ds_write2_b32 v31, v64, v65 offset1:1
	ds_write2_b32 v32, v66, v67 offset1:1
	s_waitcnt vmcnt(2)
	ds_write2_b32 v33, v68, v69 offset1:1
	ds_write2_b32 v34, v70, v71 offset1:1
	s_waitcnt vmcnt(1)
	ds_write2_b32 v35, v72, v73 offset1:1
	ds_write2_b32 v36, v74, v75 offset1:1
	s_waitcnt vmcnt(0)
	ds_write2_b32 v37, v76, v77 offset1:1
	ds_write2_b32 v38, v78, v79 offset1:1
	s_waitcnt lgkmcnt(0)
	s_barrier
	ds_read2_b32 v[208:209], v20 offset1:65
	ds_read2_b32 v[210:211], v20 offset0:130 offset1:195
	ds_read2_b32 v[212:213], v39 offset0:4 offset1:69
	ds_read2_b32 v[214:215], v39 offset0:134 offset1:199
	ds_read2_b32 v[216:217], v21 offset1:65
	ds_read2_b32 v[218:219], v21 offset0:130 offset1:195
	ds_read2_b32 v[220:221], v40 offset0:4 offset1:69
	ds_read2_b32 v[222:223], v40 offset0:134 offset1:199
	v_lshlrev_b64 v[54:55], 12, v[6:7]
	s_waitcnt lgkmcnt(7)
	v_cvt_pk_bf16_f32 v48, v208, v209
	ds_read2_b32 v[224:225], v22 offset1:65
	v_lshl_add_u64 v[54:55], s[62:63], 0, v[54:55]
	s_waitcnt lgkmcnt(7)
	v_cvt_pk_bf16_f32 v49, v210, v211
	ds_read2_b32 v[226:227], v22 offset0:130 offset1:195
	v_lshl_add_u64 v[54:55], v[54:55], 0, s[26:27]
	s_waitcnt lgkmcnt(7)
	v_cvt_pk_bf16_f32 v50, v212, v213
	ds_read2_b32 v[228:229], v41 offset0:4 offset1:69
	s_waitcnt lgkmcnt(7)
	v_cvt_pk_bf16_f32 v51, v214, v215
	ds_read2_b32 v[230:231], v41 offset0:134 offset1:199
	v_lshl_add_u64 v[56:57], v[10:11], 1, v[54:55]
	global_store_dwordx4 v[56:57], v[48:51], off
	s_nop 1
	v_lshl_add_u64 v[56:57], v[12:13], 1, v[54:55]
	s_waitcnt lgkmcnt(7)
	v_cvt_pk_bf16_f32 v48, v216, v217
	ds_read2_b32 v[232:233], v23 offset1:65
	s_waitcnt lgkmcnt(7)
	v_cvt_pk_bf16_f32 v49, v218, v219
	ds_read2_b32 v[234:235], v23 offset0:130 offset1:195
	s_waitcnt lgkmcnt(7)
	v_cvt_pk_bf16_f32 v50, v220, v221
	ds_read2_b32 v[236:237], v42 offset0:4 offset1:69
	s_waitcnt lgkmcnt(7)
	v_cvt_pk_bf16_f32 v51, v222, v223
	ds_read2_b32 v[238:239], v42 offset0:134 offset1:199
	global_store_dwordx4 v[56:57], v[48:51], off
	s_nop 1
	v_lshl_add_u64 v[56:57], v[14:15], 1, v[54:55]
	v_lshl_add_u64 v[54:55], v[16:17], 1, v[54:55]
	s_waitcnt lgkmcnt(7)
	v_cvt_pk_bf16_f32 v48, v224, v225
	s_waitcnt lgkmcnt(6)
	v_cvt_pk_bf16_f32 v49, v226, v227
	s_waitcnt lgkmcnt(5)
	v_cvt_pk_bf16_f32 v50, v228, v229
	s_waitcnt lgkmcnt(4)
	v_cvt_pk_bf16_f32 v51, v230, v231
	global_store_dwordx4 v[56:57], v[48:51], off
	s_nop 1
	s_nop 0
	s_waitcnt lgkmcnt(3)
	v_cvt_pk_bf16_f32 v48, v232, v233
	s_waitcnt lgkmcnt(2)
	v_cvt_pk_bf16_f32 v49, v234, v235
	s_waitcnt lgkmcnt(1)
	v_cvt_pk_bf16_f32 v50, v236, v237
	s_waitcnt lgkmcnt(0)
	v_cvt_pk_bf16_f32 v51, v238, v239
	global_store_dwordx4 v[54:55], v[48:51], off
	s_nop 1
	s_barrier
	s_branch .LBB0_47
; __device__ __forceinline__ unsigned cvt_pk_bf16(float lo, float hi) { unsigned r; asm volatile("v_cvt_pk_bf16_f32 %0, %1, %2" : "=v"(r) : "v"(lo), "v"(hi)); return r; }
; __device__ __forceinline__ void cvt_matrix(const float* __restrict__ src, int K, int N, bf16_t* __restrict__ dst, int kind, int& base, float* lds_f, const int wv) {
;     ...
;         const int kt = t / nnb, nb = t % nnb, k0 = kt * 256, n0 = nb * 64;
;         int drow0 = n0, perm = 0;
;         if (kind == 1) { if (n0 < DFF) drow0 = 256 * (n0 >> 7) + (n0 & 127); else { const int n1 = n0 - DFF; drow0 = 256 * (n1 >> 7) + 128 + (n1 & 127); } }
;         if (kind == 2) perm = (n0 % 192) == 128;
;         { const int c4 = tid & 15, kr = tid >> 4;
;           f32x4 v[8];
; #pragma unroll
;           for (int i = 0; i < 8; ++i) v[i] = __builtin_nontemporal_load((const f32x4*)(src + (size_t)(k0 + kr + 32 * i) * N + n0 + 4 * c4));
; #pragma unroll
;           for (int i = 0; i < 8; ++i) { float* l = lds_f + (kr + 32 * i) * 65 + 4 * c4; l[0] = v[i][0]; l[1] = v[i][1]; l[2] = v[i][2]; l[3] = v[i][3]; } }
;         __syncthreads();
; #pragma unroll
;         for (int j = 0; j < 4; ++j) { const int idx = tid + 512 * j, r = ((idx >> 6) & 3) * 16 + ((idx >> 2) & 15), kc = (idx >> 8) * 4 + (idx & 3);
;             const int sc = perm ? ((r & 1) ? 32 + (r >> 1) : (r >> 1)) : r;
;             const float* l = lds_f + (kc * 8) * 65 + sc;
;             u32x4 w; w.x = cvt_pk_bf16(l[0], l[65]); w.y = cvt_pk_bf16(l[2 * 65], l[3 * 65]); w.z = cvt_pk_bf16(l[4 * 65], l[5 * 65]); w.w = cvt_pk_bf16(l[6 * 65], l[7 * 65]);
;             *(u32x4*)(dst + (size_t)(drow0 + r) * K + k0 + kc * 8) = w; }
;         __syncthreads();
.LBB0_50:
	s_andn2_b64 vcc, exec, s[28:29]
	s_cbranch_vccnz .LBB0_45
	s_add_i32 s26, s65, s77
	s_cmpk_gt_u32 s26, 0x57f
	s_cbranch_scc1 .LBB0_45
	s_and_b32 s2, s26, 0xffff
	s_mul_i32 s2, s2, 0xba2f
	s_lshr_b32 s77, s2, 23
	s_mulk_i32 s77, 0xb0
	s_sub_i32 s26, s26, s77
	s_and_b32 s26, s26, 0xffff
	s_lshl_b32 s85, s26, 7
	s_lshr_b32 s2, s2, 15
	s_and_b32 s86, s85, 0x3f00
	s_bitset1_b32 s85, 7
	s_and_b32 s2, s2, 0xff00
	s_lshl_b32 s77, s26, 6
	s_addk_i32 s85, 0xd400
	s_cmpk_lt_u32 s26, 0x58
	s_cselect_b32 s85, s86, s85
	v_add_u32_e32 v6, s2, v18
	s_lshl_b32 s26, s26, 8
	v_lshl_add_u64 v[76:77], v[8:9], 0, s[26:27]
	v_add_u32_e32 v43, 32, v6
	v_mad_i64_i32 v[52:53], s[86:87], v43, s79, v[76:77]
	v_add_u32_e32 v43, 64, v6
	v_mad_i64_i32 v[56:57], s[86:87], v43, s79, v[76:77]
	v_add_u32_e32 v43, 0x60, v6
	v_mad_i64_i32 v[60:61], s[86:87], v43, s79, v[76:77]
	v_add_u32_e32 v43, 0x80, v6
	v_mad_i64_i32 v[64:65], s[86:87], v43, s79, v[76:77]
	v_add_u32_e32 v43, 0xa0, v6
	v_mad_i64_i32 v[48:49], s[86:87], v6, s79, v[76:77]
	v_mad_i64_i32 v[68:69], s[86:87], v43, s79, v[76:77]
	global_load_dwordx4 v[48:51], v[48:49], off nt
	s_nop 0
	global_load_dwordx4 v[52:55], v[52:53], off nt
	s_nop 0
	global_load_dwordx4 v[56:59], v[56:57], off nt
	s_nop 0
	global_load_dwordx4 v[60:63], v[60:61], off nt
	s_nop 0
	global_load_dwordx4 v[64:67], v[64:65], off nt
	s_nop 0
	global_load_dwordx4 v[68:71], v[68:69], off nt
	v_add_u32_e32 v43, 0xc0, v6
	v_mad_i64_i32 v[72:73], s[86:87], v43, s79, v[76:77]
	global_load_dwordx4 v[72:75], v[72:73], off nt
	v_add_u32_e32 v6, 0xe0, v6
	v_mad_i64_i32 v[76:77], s[86:87], v6, s79, v[76:77]
	global_load_dwordx4 v[76:79], v[76:77], off nt
	s_and_b32 s26, s77, 64
	s_or_b32 s77, s26, s85
	v_or_b32_e32 v6, s77, v19
	s_lshl_b32 s26, s2, 1
	s_waitcnt vmcnt(7)
	ds_write2_b32 v24, v48, v49 offset1:1
	ds_write2_b32 v24, v50, v51 offset0:2 offset1:3
	s_waitcnt vmcnt(6)
	ds_write2_b32 v25, v52, v53 offset1:1
	ds_write2_b32 v26, v54, v55 offset1:1
	s_waitcnt vmcnt(5)
	ds_write2_b32 v27, v56, v57 offset1:1
	ds_write2_b32 v28, v58, v59 offset1:1
	s_waitcnt vmcnt(4)
	ds_write2_b32 v29, v60, v61 offset1:1
	ds_write2_b32 v30, v62, v63 offset1:1
	s_waitcnt vmcnt(3)
	ds_write2_b32 v31, v64, v65 offset1:1
	ds_write2_b32 v32, v66, v67 offset1:1
	s_waitcnt vmcnt(2)
	ds_write2_b32 v33, v68, v69 offset1:1
	ds_write2_b32 v34, v70, v71 offset1:1
	s_waitcnt vmcnt(1)
	ds_write2_b32 v35, v72, v73 offset1:1
	ds_write2_b32 v36, v74, v75 offset1:1
	s_waitcnt vmcnt(0)
	ds_write2_b32 v37, v76, v77 offset1:1
	ds_write2_b32 v38, v78, v79 offset1:1
	s_waitcnt lgkmcnt(0)
	s_barrier
	ds_read2_b32 v[208:209], v20 offset1:65
	ds_read2_b32 v[210:211], v20 offset0:130 offset1:195
	ds_read2_b32 v[212:213], v39 offset0:4 offset1:69
	ds_read2_b32 v[214:215], v39 offset0:134 offset1:199
	ds_read2_b32 v[216:217], v21 offset1:65
	ds_read2_b32 v[218:219], v21 offset0:130 offset1:195
	ds_read2_b32 v[220:221], v40 offset0:4 offset1:69
	ds_read2_b32 v[222:223], v40 offset0:134 offset1:199
	v_lshlrev_b64 v[54:55], 12, v[6:7]
	s_waitcnt lgkmcnt(7)
	v_cvt_pk_bf16_f32 v48, v208, v209
	ds_read2_b32 v[224:225], v22 offset1:65
	v_lshl_add_u64 v[54:55], s[62:63], 0, v[54:55]
	s_waitcnt lgkmcnt(7)
	v_cvt_pk_bf16_f32 v49, v210, v211
	ds_read2_b32 v[226:227], v22 offset0:130 offset1:195
	v_lshl_add_u64 v[54:55], v[54:55], 0, s[26:27]
	s_waitcnt lgkmcnt(7)
	v_cvt_pk_bf16_f32 v50, v212, v213
	ds_read2_b32 v[228:229], v41 offset0:4 offset1:69
	s_waitcnt lgkmcnt(7)
	v_cvt_pk_bf16_f32 v51, v214, v215
	ds_read2_b32 v[230:231], v41 offset0:134 offset1:199
	v_lshl_add_u64 v[56:57], v[10:11], 1, v[54:55]
	global_store_dwordx4 v[56:57], v[48:51], off
	s_nop 1
	v_lshl_add_u64 v[56:57], v[12:13], 1, v[54:55]
	s_waitcnt lgkmcnt(7)
	v_cvt_pk_bf16_f32 v48, v216, v217
	ds_read2_b32 v[232:233], v23 offset1:65
	s_waitcnt lgkmcnt(7)
	v_cvt_pk_bf16_f32 v49, v218, v219
	ds_read2_b32 v[234:235], v23 offset0:130 offset1:195
	s_waitcnt lgkmcnt(7)
	v_cvt_pk_bf16_f32 v50, v220, v221
	ds_read2_b32 v[236:237], v42 offset0:4 offset1:69
	s_waitcnt lgkmcnt(7)
	v_cvt_pk_bf16_f32 v51, v222, v223
	ds_read2_b32 v[238:239], v42 offset0:134 offset1:199
	global_store_dwordx4 v[56:57], v[48:51], off
	s_nop 1
	v_lshl_add_u64 v[56:57], v[14:15], 1, v[54:55]
	v_lshl_add_u64 v[54:55], v[16:17], 1, v[54:55]
	s_waitcnt lgkmcnt(7)
	v_cvt_pk_bf16_f32 v48, v224, v225
	s_waitcnt lgkmcnt(6)
	v_cvt_pk_bf16_f32 v49, v226, v227
	s_waitcnt lgkmcnt(5)
	v_cvt_pk_bf16_f32 v50, v228, v229
	s_waitcnt lgkmcnt(4)
	v_cvt_pk_bf16_f32 v51, v230, v231
	global_store_dwordx4 v[56:57], v[48:51], off
	s_nop 1
	s_nop 0
	s_waitcnt lgkmcnt(3)
	v_cvt_pk_bf16_f32 v48, v232, v233
	s_waitcnt lgkmcnt(2)
	v_cvt_pk_bf16_f32 v49, v234, v235
	s_waitcnt lgkmcnt(1)
	v_cvt_pk_bf16_f32 v50, v236, v237
	s_waitcnt lgkmcnt(0)
	v_cvt_pk_bf16_f32 v51, v238, v239
	global_store_dwordx4 v[54:55], v[48:51], off
	s_nop 1
	s_barrier
	s_branch .LBB0_45

; __device__ __forceinline__ unsigned cvt_pk_bf16(float lo, float hi) { unsigned r; asm volatile("v_cvt_pk_bf16_f32 %0, %1, %2" : "=v"(r) : "v"(lo), "v"(hi)); return r; }
; __device__ __forceinline__ void cvt_matrix(const float* __restrict__ src, int K, int N, bf16_t* __restrict__ dst, int kind, int& base, float* lds_f, const int wv) {
;     ...
;         const int kt = t / nnb, nb = t % nnb, k0 = kt * 256, n0 = nb * 64;
;         int drow0 = n0, perm = 0;
;         if (kind == 1) { if (n0 < DFF) drow0 = 256 * (n0 >> 7) + (n0 & 127); else { const int n1 = n0 - DFF; drow0 = 256 * (n1 >> 7) + 128 + (n1 & 127); } }
;         if (kind == 2) perm = (n0 % 192) == 128;
;         { const int c4 = tid & 15, kr = tid >> 4;
;           f32x4 v[8];
; #pragma unroll
;           for (int i = 0; i < 8; ++i) v[i] = __builtin_nontemporal_load((const f32x4*)(src + (size_t)(k0 + kr + 32 * i) * N + n0 + 4 * c4));
; #pragma unroll
;           for (int i = 0; i < 8; ++i) { float* l = lds_f + (kr + 32 * i) * 65 + 4 * c4; l[0] = v[i][0]; l[1] = v[i][1]; l[2] = v[i][2]; l[3] = v[i][3]; } }
;         __syncthreads();
; #pragma unroll
;         for (int j = 0; j < 4; ++j) { const int idx = tid + 512 * j, r = ((idx >> 6) & 3) * 16 + ((idx >> 2) & 15), kc = (idx >> 8) * 4 + (idx & 3);
;             const int sc = perm ? ((r & 1) ? 32 + (r >> 1) : (r >> 1)) : r;
;             const float* l = lds_f + (kc * 8) * 65 + sc;
;             u32x4 w; w.x = cvt_pk_bf16(l[0], l[65]); w.y = cvt_pk_bf16(l[2 * 65], l[3 * 65]); w.z = cvt_pk_bf16(l[4 * 65], l[5 * 65]); w.w = cvt_pk_bf16(l[6 * 65], l[7 * 65]);
;             *(u32x4*)(dst + (size_t)(drow0 + r) * K + k0 + kc * 8) = w; }
;         __syncthreads();
.LBB0_58:
	s_cmpk_gt_u32 s67, 0x57f
	s_cbranch_scc1 .LBB0_57
	s_and_b32 s2, s67, 0xffff
	s_mul_i32 s2, s2, 0xba2f
	s_lshr_b32 s26, s2, 23
	s_mulk_i32 s26, 0xb0
	s_sub_i32 s26, s67, s26
	s_and_b32 s26, s26, 0xffff
	s_lshl_b32 s88, s26, 7
	s_lshr_b32 s2, s2, 15
	s_or_b32 s89, s88, 0x80
	s_and_b32 s2, s2, 0xff00
	s_lshl_b32 s87, s26, 6
	s_addk_i32 s89, 0xd400
	s_and_b32 s88, s88, 0x3f00
	s_cmpk_lt_u32 s26, 0x58
	s_cselect_b32 s90, s88, s89
	v_add_u32_e32 v6, s2, v18
	s_lshl_b32 s26, s26, 8
	v_lshl_add_u64 v[42:43], v[8:9], 0, s[26:27]
	v_add_u32_e32 v28, 32, v6
	v_add_u32_e32 v34, 64, v6
	v_add_u32_e32 v36, 0x60, v6
	v_add_u32_e32 v48, 0x80, v6
	v_add_u32_e32 v50, 0xa0, v6
	v_mad_i64_i32 v[26:27], s[88:89], v6, s79, v[42:43]
	v_mad_i64_i32 v[30:31], s[88:89], v28, s79, v[42:43]
	v_mad_i64_i32 v[34:35], s[88:89], v34, s79, v[42:43]
	v_mad_i64_i32 v[38:39], s[88:89], v36, s79, v[42:43]
	v_mad_i64_i32 v[48:49], s[88:89], v48, s79, v[42:43]
	v_mad_i64_i32 v[52:53], s[88:89], v50, s79, v[42:43]
	global_load_dwordx4 v[26:29], v[26:27], off nt
	s_nop 0
	global_load_dwordx4 v[30:33], v[30:31], off nt
	s_nop 0
	global_load_dwordx4 v[34:37], v[34:35], off nt
	s_nop 0
	global_load_dwordx4 v[38:41], v[38:39], off nt
	s_nop 0
	global_load_dwordx4 v[48:51], v[48:49], off nt
	s_nop 0
	global_load_dwordx4 v[52:55], v[52:53], off nt
	v_add_u32_e32 v56, 0xc0, v6
	v_mad_i64_i32 v[56:57], s[88:89], v56, s79, v[42:43]
	global_load_dwordx4 v[56:59], v[56:57], off nt
	v_add_u32_e32 v6, 0xe0, v6
	v_mad_i64_i32 v[42:43], s[88:89], v6, s79, v[42:43]
	global_load_dwordx4 v[60:63], v[42:43], off nt
	v_add_u32_e32 v6, v19, v21
	v_add_u32_e32 v42, 0x2080, v6
	v_add_u32_e32 v43, 0x2088, v6
	v_add_u32_e32 v64, 0x4100, v6
	v_add_u32_e32 v65, 0x4108, v6
	v_add_u32_e32 v66, 0x6180, v6
	v_add_u32_e32 v67, 0x6188, v6
	v_add_u32_e32 v68, 0x8200, v6
	v_add_u32_e32 v69, 0x8208, v6
	v_add_u32_e32 v70, 0xa280, v6
	v_add_u32_e32 v71, 0xa288, v6
	v_add_u32_e32 v72, 0xc300, v6
	v_add_u32_e32 v73, 0xc308, v6
	v_add_u32_e32 v74, 0xe380, v6
	v_add_u32_e32 v75, 0xe388, v6
	s_and_b32 s26, s87, 64
	s_or_b32 s87, s26, s90
	s_lshl_b32 s26, s2, 1
	s_waitcnt vmcnt(7)
	ds_write2_b32 v6, v26, v27 offset1:1
	ds_write2_b32 v6, v28, v29 offset0:2 offset1:3
	s_waitcnt vmcnt(6)
	ds_write2_b32 v42, v30, v31 offset1:1
	ds_write2_b32 v43, v32, v33 offset1:1
	s_waitcnt vmcnt(5)
	ds_write2_b32 v64, v34, v35 offset1:1
	ds_write2_b32 v65, v36, v37 offset1:1
	s_waitcnt vmcnt(4)
	ds_write2_b32 v66, v38, v39 offset1:1
	ds_write2_b32 v67, v40, v41 offset1:1
	s_waitcnt vmcnt(3)
	ds_write2_b32 v68, v48, v49 offset1:1
	ds_write2_b32 v69, v50, v51 offset1:1
	s_waitcnt vmcnt(2)
	ds_write2_b32 v70, v52, v53 offset1:1
	ds_write2_b32 v71, v54, v55 offset1:1
	s_waitcnt vmcnt(1)
	ds_write2_b32 v72, v56, v57 offset1:1
	ds_write2_b32 v73, v58, v59 offset1:1
	s_waitcnt vmcnt(0)
	ds_write2_b32 v74, v60, v61 offset1:1
	ds_write2_b32 v75, v62, v63 offset1:1
	s_waitcnt lgkmcnt(0)
	s_barrier
	ds_read2_b32 v[208:209], v22 offset1:65
	ds_read2_b32 v[210:211], v22 offset0:130 offset1:195
	v_add_u32_e32 v200, 0x400, v22
	ds_read2_b32 v[212:213], v200 offset0:4 offset1:69
	ds_read2_b32 v[214:215], v200 offset0:134 offset1:199
	ds_read2_b32 v[216:217], v23 offset1:65
	v_add_u32_e32 v201, 0x400, v23
	ds_read2_b32 v[218:219], v23 offset0:130 offset1:195
	ds_read2_b32 v[220:221], v201 offset0:4 offset1:69
	ds_read2_b32 v[222:223], v201 offset0:134 offset1:199
	s_waitcnt lgkmcnt(7)
	v_cvt_pk_bf16_f32 v26, v208, v209
	ds_read2_b32 v[224:225], v24 offset1:65
	s_waitcnt lgkmcnt(7)
	v_cvt_pk_bf16_f32 v27, v210, v211
	v_add_u32_e32 v202, 0x400, v24
	ds_read2_b32 v[226:227], v24 offset0:130 offset1:195
	s_waitcnt lgkmcnt(7)
	v_cvt_pk_bf16_f32 v28, v212, v213
	ds_read2_b32 v[228:229], v202 offset0:4 offset1:69
	v_or_b32_e32 v6, s87, v20
	v_lshlrev_b64 v[32:33], 12, v[6:7]
	v_lshl_add_u64 v[32:33], s[64:65], 0, v[32:33]
	v_lshl_add_u64 v[32:33], v[32:33], 0, s[26:27]
	s_waitcnt lgkmcnt(7)
	v_cvt_pk_bf16_f32 v29, v214, v215
	ds_read2_b32 v[230:231], v202 offset0:134 offset1:199
	v_lshl_add_u64 v[34:35], v[10:11], 1, v[32:33]
	global_store_dwordx4 v[34:35], v[26:29], off
	s_nop 1
	v_lshl_add_u64 v[34:35], v[12:13], 1, v[32:33]
	s_waitcnt lgkmcnt(7)
	v_cvt_pk_bf16_f32 v26, v216, v217
	ds_read2_b32 v[232:233], v25 offset1:65
	s_waitcnt lgkmcnt(7)
	v_cvt_pk_bf16_f32 v27, v218, v219
	v_add_u32_e32 v203, 0x400, v25
	ds_read2_b32 v[234:235], v25 offset0:130 offset1:195
	s_waitcnt lgkmcnt(7)
	v_cvt_pk_bf16_f32 v28, v220, v221
	ds_read2_b32 v[236:237], v203 offset0:4 offset1:69
	s_waitcnt lgkmcnt(7)
	v_cvt_pk_bf16_f32 v29, v222, v223
	ds_read2_b32 v[238:239], v203 offset0:134 offset1:199
	global_store_dwordx4 v[34:35], v[26:29], off
	s_nop 1
	v_lshl_add_u64 v[34:35], v[14:15], 1, v[32:33]
	s_waitcnt lgkmcnt(7)
	v_cvt_pk_bf16_f32 v26, v224, v225
	s_waitcnt lgkmcnt(6)
	v_cvt_pk_bf16_f32 v27, v226, v227
	s_waitcnt lgkmcnt(5)
	v_cvt_pk_bf16_f32 v28, v228, v229
	s_waitcnt lgkmcnt(4)
	v_cvt_pk_bf16_f32 v29, v230, v231
	global_store_dwordx4 v[34:35], v[26:29], off
	s_nop 1
	v_lshl_add_u64 v[32:33], v[16:17], 1, v[32:33]
	s_waitcnt lgkmcnt(3)
	v_cvt_pk_bf16_f32 v26, v232, v233
	s_waitcnt lgkmcnt(2)
	v_cvt_pk_bf16_f32 v27, v234, v235
	s_waitcnt lgkmcnt(1)
	v_cvt_pk_bf16_f32 v28, v236, v237
	s_waitcnt lgkmcnt(0)
	v_cvt_pk_bf16_f32 v29, v238, v239
	global_store_dwordx4 v[32:33], v[26:29], off
	s_nop 1
	s_barrier
	s_branch .LBB0_57
; __device__ __forceinline__ unsigned cvt_pk_bf16(float lo, float hi) { unsigned r; asm volatile("v_cvt_pk_bf16_f32 %0, %1, %2" : "=v"(r) : "v"(lo), "v"(hi)); return r; }
; __device__ __forceinline__ void cvt_matrix(const float* __restrict__ src, int K, int N, bf16_t* __restrict__ dst, int kind, int& base, float* lds_f, const int wv) {
;     ...
;         const int kt = t / nnb, nb = t % nnb, k0 = kt * 256, n0 = nb * 64;
;         int drow0 = n0, perm = 0;
;         if (kind == 1) { if (n0 < DFF) drow0 = 256 * (n0 >> 7) + (n0 & 127); else { const int n1 = n0 - DFF; drow0 = 256 * (n1 >> 7) + 128 + (n1 & 127); } }
;         if (kind == 2) perm = (n0 % 192) == 128;
;         { const int c4 = tid & 15, kr = tid >> 4;
;           f32x4 v[8];
; #pragma unroll
;           for (int i = 0; i < 8; ++i) v[i] = __builtin_nontemporal_load((const f32x4*)(src + (size_t)(k0 + kr + 32 * i) * N + n0 + 4 * c4));
; #pragma unroll
;           for (int i = 0; i < 8; ++i) { float* l = lds_f + (kr + 32 * i) * 65 + 4 * c4; l[0] = v[i][0]; l[1] = v[i][1]; l[2] = v[i][2]; l[3] = v[i][3]; } }
;         __syncthreads();
; #pragma unroll
;         for (int j = 0; j < 4; ++j) { const int idx = tid + 512 * j, r = ((idx >> 6) & 3) * 16 + ((idx >> 2) & 15), kc = (idx >> 8) * 4 + (idx & 3);
;             const int sc = perm ? ((r & 1) ? 32 + (r >> 1) : (r >> 1)) : r;
;             const float* l = lds_f + (kc * 8) * 65 + sc;
;             u32x4 w; w.x = cvt_pk_bf16(l[0], l[65]); w.y = cvt_pk_bf16(l[2 * 65], l[3 * 65]); w.z = cvt_pk_bf16(l[4 * 65], l[5 * 65]); w.w = cvt_pk_bf16(l[6 * 65], l[7 * 65]);
;             *(u32x4*)(dst + (size_t)(drow0 + r) * K + k0 + kc * 8) = w; }
;         __syncthreads();
.LBB0_60:
	s_andn2_b64 vcc, exec, s[28:29]
	s_cbranch_vccnz .LBB0_55
	s_add_i32 s26, s66, s85
	s_cmpk_gt_u32 s26, 0x57f
	s_cbranch_scc1 .LBB0_55
	s_and_b32 s2, s26, 0xffff
	s_mul_i32 s2, s2, 0xba2f
	s_lshr_b32 s67, s2, 23
	s_mulk_i32 s67, 0xb0
	s_sub_i32 s26, s26, s67
	s_and_b32 s26, s26, 0xffff
	s_lshl_b32 s85, s26, 7
	s_lshr_b32 s2, s2, 15
	s_and_b32 s86, s85, 0x3f00
	s_bitset1_b32 s85, 7
	s_and_b32 s2, s2, 0xff00
	s_lshl_b32 s67, s26, 6
	s_addk_i32 s85, 0xd400
	s_cmpk_lt_u32 s26, 0x58
	s_cselect_b32 s85, s86, s85
	v_add_u32_e32 v6, s2, v18
	s_lshl_b32 s26, s26, 8
	v_lshl_add_u64 v[42:43], v[8:9], 0, s[26:27]
	v_add_u32_e32 v28, 32, v6
	v_add_u32_e32 v34, 64, v6
	v_add_u32_e32 v36, 0x60, v6
	v_add_u32_e32 v48, 0x80, v6
	v_add_u32_e32 v50, 0xa0, v6
	v_mad_i64_i32 v[26:27], s[86:87], v6, s79, v[42:43]
	v_mad_i64_i32 v[30:31], s[86:87], v28, s79, v[42:43]
	v_mad_i64_i32 v[34:35], s[86:87], v34, s79, v[42:43]
	v_mad_i64_i32 v[38:39], s[86:87], v36, s79, v[42:43]
	v_mad_i64_i32 v[48:49], s[86:87], v48, s79, v[42:43]
	v_mad_i64_i32 v[52:53], s[86:87], v50, s79, v[42:43]
	global_load_dwordx4 v[26:29], v[26:27], off nt
	s_nop 0
	global_load_dwordx4 v[30:33], v[30:31], off nt
	s_nop 0
	global_load_dwordx4 v[34:37], v[34:35], off nt
	s_nop 0
	global_load_dwordx4 v[38:41], v[38:39], off nt
	s_nop 0
	global_load_dwordx4 v[48:51], v[48:49], off nt
	s_nop 0
	global_load_dwordx4 v[52:55], v[52:53], off nt
	v_add_u32_e32 v56, 0xc0, v6
	v_mad_i64_i32 v[56:57], s[86:87], v56, s79, v[42:43]
	global_load_dwordx4 v[56:59], v[56:57], off nt
	v_add_u32_e32 v6, 0xe0, v6
	v_mad_i64_i32 v[42:43], s[86:87], v6, s79, v[42:43]
	global_load_dwordx4 v[60:63], v[42:43], off nt
	v_add_u32_e32 v6, v19, v21
	v_add_u32_e32 v42, 0x2080, v6
	v_add_u32_e32 v43, 0x2088, v6
	v_add_u32_e32 v64, 0x4100, v6
	v_add_u32_e32 v65, 0x4108, v6
	v_add_u32_e32 v66, 0x6180, v6
	v_add_u32_e32 v67, 0x6188, v6
	v_add_u32_e32 v68, 0x8200, v6
	v_add_u32_e32 v69, 0x8208, v6
	v_add_u32_e32 v70, 0xa280, v6
	v_add_u32_e32 v71, 0xa288, v6
	v_add_u32_e32 v72, 0xc300, v6
	v_add_u32_e32 v73, 0xc308, v6
	v_add_u32_e32 v74, 0xe380, v6
	v_add_u32_e32 v75, 0xe388, v6
	s_and_b32 s26, s67, 64
	s_or_b32 s67, s26, s85
	s_lshl_b32 s26, s2, 1
	s_waitcnt vmcnt(7)
	ds_write2_b32 v6, v26, v27 offset1:1
	ds_write2_b32 v6, v28, v29 offset0:2 offset1:3
	s_waitcnt vmcnt(6)
	ds_write2_b32 v42, v30, v31 offset1:1
	ds_write2_b32 v43, v32, v33 offset1:1
	s_waitcnt vmcnt(5)
	ds_write2_b32 v64, v34, v35 offset1:1
	ds_write2_b32 v65, v36, v37 offset1:1
	s_waitcnt vmcnt(4)
	ds_write2_b32 v66, v38, v39 offset1:1
	ds_write2_b32 v67, v40, v41 offset1:1
	s_waitcnt vmcnt(3)
	ds_write2_b32 v68, v48, v49 offset1:1
	ds_write2_b32 v69, v50, v51 offset1:1
	s_waitcnt vmcnt(2)
	ds_write2_b32 v70, v52, v53 offset1:1
	ds_write2_b32 v71, v54, v55 offset1:1
	s_waitcnt vmcnt(1)
	ds_write2_b32 v72, v56, v57 offset1:1
	ds_write2_b32 v73, v58, v59 offset1:1
	s_waitcnt vmcnt(0)
	ds_write2_b32 v74, v60, v61 offset1:1
	ds_write2_b32 v75, v62, v63 offset1:1
	s_waitcnt lgkmcnt(0)
	s_barrier
	ds_read2_b32 v[208:209], v22 offset1:65
	ds_read2_b32 v[210:211], v22 offset0:130 offset1:195
	v_add_u32_e32 v200, 0x400, v22
	ds_read2_b32 v[212:213], v200 offset0:4 offset1:69
	ds_read2_b32 v[214:215], v200 offset0:134 offset1:199
	ds_read2_b32 v[216:217], v23 offset1:65
	v_add_u32_e32 v201, 0x400, v23
	ds_read2_b32 v[218:219], v23 offset0:130 offset1:195
	ds_read2_b32 v[220:221], v201 offset0:4 offset1:69
	ds_read2_b32 v[222:223], v201 offset0:134 offset1:199
	s_waitcnt lgkmcnt(7)
	v_cvt_pk_bf16_f32 v26, v208, v209
	ds_read2_b32 v[224:225], v24 offset1:65
	s_waitcnt lgkmcnt(7)
	v_cvt_pk_bf16_f32 v27, v210, v211
	v_add_u32_e32 v202, 0x400, v24
	ds_read2_b32 v[226:227], v24 offset0:130 offset1:195
	s_waitcnt lgkmcnt(7)
	v_cvt_pk_bf16_f32 v28, v212, v213
	ds_read2_b32 v[228:229], v202 offset0:4 offset1:69
	v_or_b32_e32 v6, s67, v20
	v_lshlrev_b64 v[32:33], 12, v[6:7]
	v_lshl_add_u64 v[32:33], s[64:65], 0, v[32:33]
	v_lshl_add_u64 v[32:33], v[32:33], 0, s[26:27]
	s_waitcnt lgkmcnt(7)
	v_cvt_pk_bf16_f32 v29, v214, v215
	ds_read2_b32 v[230:231], v202 offset0:134 offset1:199
	v_lshl_add_u64 v[34:35], v[10:11], 1, v[32:33]
	global_store_dwordx4 v[34:35], v[26:29], off
	s_nop 1
	v_lshl_add_u64 v[34:35], v[12:13], 1, v[32:33]
	s_waitcnt lgkmcnt(7)
	v_cvt_pk_bf16_f32 v26, v216, v217
	ds_read2_b32 v[232:233], v25 offset1:65
	s_waitcnt lgkmcnt(7)
	v_cvt_pk_bf16_f32 v27, v218, v219
	v_add_u32_e32 v203, 0x400, v25
	ds_read2_b32 v[234:235], v25 offset0:130 offset1:195
	s_waitcnt lgkmcnt(7)
	v_cvt_pk_bf16_f32 v28, v220, v221
	ds_read2_b32 v[236:237], v203 offset0:4 offset1:69
	s_waitcnt lgkmcnt(7)
	v_cvt_pk_bf16_f32 v29, v222, v223
	ds_read2_b32 v[238:239], v203 offset0:134 offset1:199
	global_store_dwordx4 v[34:35], v[26:29], off
	s_nop 1
	v_lshl_add_u64 v[34:35], v[14:15], 1, v[32:33]
	s_waitcnt lgkmcnt(7)
	v_cvt_pk_bf16_f32 v26, v224, v225
	s_waitcnt lgkmcnt(6)
	v_cvt_pk_bf16_f32 v27, v226, v227
	s_waitcnt lgkmcnt(5)
	v_cvt_pk_bf16_f32 v28, v228, v229
	s_waitcnt lgkmcnt(4)
	v_cvt_pk_bf16_f32 v29, v230, v231
	global_store_dwordx4 v[34:35], v[26:29], off
	s_nop 1
	v_lshl_add_u64 v[32:33], v[16:17], 1, v[32:33]
	s_waitcnt lgkmcnt(3)
	v_cvt_pk_bf16_f32 v26, v232, v233
	s_waitcnt lgkmcnt(2)
	v_cvt_pk_bf16_f32 v27, v234, v235
	s_waitcnt lgkmcnt(1)
	v_cvt_pk_bf16_f32 v28, v236, v237
	s_waitcnt lgkmcnt(0)
	v_cvt_pk_bf16_f32 v29, v238, v239
	global_store_dwordx4 v[32:33], v[26:29], off
	s_nop 1
	s_barrier
	s_branch .LBB0_55

; __device__ __forceinline__ unsigned cvt_pk_bf16(float lo, float hi) { unsigned r; asm volatile("v_cvt_pk_bf16_f32 %0, %1, %2" : "=v"(r) : "v"(lo), "v"(hi)); return r; }
; __device__ __forceinline__ void cvt_matrix(const float* __restrict__ src, int K, int N, bf16_t* __restrict__ dst, int kind, int& base, float* lds_f, const int wv) {
;     ...
;         const int kt = t / nnb, nb = t % nnb, k0 = kt * 256, n0 = nb * 64;
;         int drow0 = n0, perm = 0;
;         if (kind == 1) { if (n0 < DFF) drow0 = 256 * (n0 >> 7) + (n0 & 127); else { const int n1 = n0 - DFF; drow0 = 256 * (n1 >> 7) + 128 + (n1 & 127); } }
;         if (kind == 2) perm = (n0 % 192) == 128;
;         { const int c4 = tid & 15, kr = tid >> 4;
;           f32x4 v[8];
; #pragma unroll
;           for (int i = 0; i < 8; ++i) v[i] = __builtin_nontemporal_load((const f32x4*)(src + (size_t)(k0 + kr + 32 * i) * N + n0 + 4 * c4));
; #pragma unroll
;           for (int i = 0; i < 8; ++i) { float* l = lds_f + (kr + 32 * i) * 65 + 4 * c4; l[0] = v[i][0]; l[1] = v[i][1]; l[2] = v[i][2]; l[3] = v[i][3]; } }
;         __syncthreads();
; #pragma unroll
;         for (int j = 0; j < 4; ++j) { const int idx = tid + 512 * j, r = ((idx >> 6) & 3) * 16 + ((idx >> 2) & 15), kc = (idx >> 8) * 4 + (idx & 3);
;             const int sc = perm ? ((r & 1) ? 32 + (r >> 1) : (r >> 1)) : r;
;             const float* l = lds_f + (kc * 8) * 65 + sc;
;             u32x4 w; w.x = cvt_pk_bf16(l[0], l[65]); w.y = cvt_pk_bf16(l[2 * 65], l[3 * 65]); w.z = cvt_pk_bf16(l[4 * 65], l[5 * 65]); w.w = cvt_pk_bf16(l[6 * 65], l[7 * 65]);
;             *(u32x4*)(dst + (size_t)(drow0 + r) * K + k0 + kc * 8) = w; }
;         __syncthreads();
.LBB0_68:
	s_cmpk_gt_u32 s87, 0x2bf
	s_cbranch_scc1 .LBB0_67
	s_and_b32 s2, s89, 0x1f00
	s_and_b32 s91, s90, 0x7c0
	v_add_u32_e32 v26, s2, v18
	s_lshl_b32 s26, s91, 2
	v_ashrrev_i32_e32 v27, 31, v26
	v_lshl_add_u64 v[28:29], v[8:9], 0, s[26:27]
	v_lshlrev_b64 v[26:27], 13, v[26:27]
	v_lshl_add_u64 v[42:43], v[28:29], 0, v[26:27]
	v_add_co_u32_e32 v30, vcc, 0x40000, v42
	v_add_u32_e32 v6, v19, v21
	s_nop 0
	v_addc_co_u32_e32 v31, vcc, 0, v43, vcc
	v_add_co_u32_e32 v34, vcc, 0x80000, v42
	global_load_dwordx4 v[26:29], v[42:43], off nt
	s_nop 0
	global_load_dwordx4 v[30:33], v[30:31], off nt
	v_addc_co_u32_e32 v35, vcc, 0, v43, vcc
	v_add_co_u32_e32 v38, vcc, 0xc0000, v42
	v_add_u32_e32 v64, 0x4100, v6
	s_nop 0
	v_addc_co_u32_e32 v39, vcc, 0, v43, vcc
	v_add_co_u32_e32 v48, vcc, 0x100000, v42
	global_load_dwordx4 v[34:37], v[34:35], off nt
	s_nop 0
	global_load_dwordx4 v[38:41], v[38:39], off nt
	v_addc_co_u32_e32 v49, vcc, 0, v43, vcc
	v_add_co_u32_e32 v52, vcc, 0x140000, v42
	v_add_u32_e32 v65, 0x4108, v6
	s_nop 0
	v_addc_co_u32_e32 v53, vcc, 0, v43, vcc
	global_load_dwordx4 v[48:51], v[48:49], off nt
	s_nop 0
	global_load_dwordx4 v[52:55], v[52:53], off nt
	v_add_co_u32_e32 v56, vcc, 0x180000, v42
	v_add_u32_e32 v66, 0x6180, v6
	s_nop 0
	v_addc_co_u32_e32 v57, vcc, 0, v43, vcc
	global_load_dwordx4 v[56:59], v[56:57], off nt
	v_add_co_u32_e32 v42, vcc, 0x1c0000, v42
	v_add_u32_e32 v67, 0x6188, v6
	s_nop 0
	v_addc_co_u32_e32 v43, vcc, 0, v43, vcc
	global_load_dwordx4 v[60:63], v[42:43], off nt
	v_add_u32_e32 v42, 0x2080, v6
	v_add_u32_e32 v43, 0x2088, v6
	v_add_u32_e32 v68, 0x8200, v6
	v_add_u32_e32 v69, 0x8208, v6
	v_add_u32_e32 v70, 0xa280, v6
	v_add_u32_e32 v71, 0xa288, v6
	v_add_u32_e32 v72, 0xc300, v6
	v_add_u32_e32 v73, 0xc308, v6
	v_add_u32_e32 v74, 0xe380, v6
	v_add_u32_e32 v75, 0xe388, v6
	s_lshl_b32 s26, s2, 1
	s_waitcnt vmcnt(7)
	ds_write2_b32 v6, v26, v27 offset1:1
	ds_write2_b32 v6, v28, v29 offset0:2 offset1:3
	s_waitcnt vmcnt(6)
	ds_write2_b32 v42, v30, v31 offset1:1
	ds_write2_b32 v43, v32, v33 offset1:1
	s_waitcnt vmcnt(5)
	ds_write2_b32 v64, v34, v35 offset1:1
	ds_write2_b32 v65, v36, v37 offset1:1
	s_waitcnt vmcnt(4)
	ds_write2_b32 v66, v38, v39 offset1:1
	ds_write2_b32 v67, v40, v41 offset1:1
	s_waitcnt vmcnt(3)
	ds_write2_b32 v68, v48, v49 offset1:1
	ds_write2_b32 v69, v50, v51 offset1:1
	s_waitcnt vmcnt(2)
	ds_write2_b32 v70, v52, v53 offset1:1
	ds_write2_b32 v71, v54, v55 offset1:1
	s_waitcnt vmcnt(1)
	ds_write2_b32 v72, v56, v57 offset1:1
	ds_write2_b32 v73, v58, v59 offset1:1
	s_waitcnt vmcnt(0)
	ds_write2_b32 v74, v60, v61 offset1:1
	ds_write2_b32 v75, v62, v63 offset1:1
	s_waitcnt lgkmcnt(0)
	s_barrier
	ds_read2_b32 v[208:209], v22 offset1:65
	ds_read2_b32 v[210:211], v22 offset0:130 offset1:195
	v_add_u32_e32 v200, 0x400, v22
	ds_read2_b32 v[212:213], v200 offset0:4 offset1:69
	ds_read2_b32 v[214:215], v200 offset0:134 offset1:199
	ds_read2_b32 v[216:217], v23 offset1:65
	v_add_u32_e32 v201, 0x400, v23
	ds_read2_b32 v[218:219], v23 offset0:130 offset1:195
	ds_read2_b32 v[220:221], v201 offset0:4 offset1:69
	ds_read2_b32 v[222:223], v201 offset0:134 offset1:199
	s_waitcnt lgkmcnt(7)
	v_cvt_pk_bf16_f32 v26, v208, v209
	ds_read2_b32 v[224:225], v24 offset1:65
	s_waitcnt lgkmcnt(7)
	v_cvt_pk_bf16_f32 v27, v210, v211
	v_add_u32_e32 v202, 0x400, v24
	ds_read2_b32 v[226:227], v24 offset0:130 offset1:195
	s_waitcnt lgkmcnt(7)
	v_cvt_pk_bf16_f32 v28, v212, v213
	ds_read2_b32 v[228:229], v202 offset0:4 offset1:69
	v_or_b32_e32 v6, s91, v20
	v_mul_u32_u24_e32 v6, 0x1600, v6
	v_lshlrev_b32_e32 v6, 1, v6
	v_lshl_add_u64 v[32:33], s[66:67], 0, v[6:7]
	v_lshl_add_u64 v[32:33], v[32:33], 0, s[26:27]
	s_waitcnt lgkmcnt(7)
	v_cvt_pk_bf16_f32 v29, v214, v215
	ds_read2_b32 v[230:231], v202 offset0:134 offset1:199
	v_lshl_add_u64 v[34:35], v[10:11], 1, v[32:33]
	global_store_dwordx4 v[34:35], v[26:29], off
	s_nop 1
	v_lshl_add_u64 v[34:35], v[12:13], 1, v[32:33]
	s_waitcnt lgkmcnt(7)
	v_cvt_pk_bf16_f32 v26, v216, v217
	ds_read2_b32 v[232:233], v25 offset1:65
	s_waitcnt lgkmcnt(7)
	v_cvt_pk_bf16_f32 v27, v218, v219
	v_add_u32_e32 v203, 0x400, v25
	ds_read2_b32 v[234:235], v25 offset0:130 offset1:195
	s_waitcnt lgkmcnt(7)
	v_cvt_pk_bf16_f32 v28, v220, v221
	ds_read2_b32 v[236:237], v203 offset0:4 offset1:69
	s_waitcnt lgkmcnt(7)
	v_cvt_pk_bf16_f32 v29, v222, v223
	ds_read2_b32 v[238:239], v203 offset0:134 offset1:199
	global_store_dwordx4 v[34:35], v[26:29], off
	s_nop 1
	v_lshl_add_u64 v[34:35], v[14:15], 1, v[32:33]
	s_waitcnt lgkmcnt(7)
	v_cvt_pk_bf16_f32 v26, v224, v225
	s_waitcnt lgkmcnt(6)
	v_cvt_pk_bf16_f32 v27, v226, v227
	s_waitcnt lgkmcnt(5)
	v_cvt_pk_bf16_f32 v28, v228, v229
	s_waitcnt lgkmcnt(4)
	v_cvt_pk_bf16_f32 v29, v230, v231
	global_store_dwordx4 v[34:35], v[26:29], off
	s_nop 1
	v_lshl_add_u64 v[32:33], v[16:17], 1, v[32:33]
	s_waitcnt lgkmcnt(3)
	v_cvt_pk_bf16_f32 v26, v232, v233
	s_waitcnt lgkmcnt(2)
	v_cvt_pk_bf16_f32 v27, v234, v235
	s_waitcnt lgkmcnt(1)
	v_cvt_pk_bf16_f32 v28, v236, v237
	s_waitcnt lgkmcnt(0)
	v_cvt_pk_bf16_f32 v29, v238, v239
	global_store_dwordx4 v[32:33], v[26:29], off
	s_nop 1
	s_barrier
	s_branch .LBB0_67
; __device__ __forceinline__ unsigned cvt_pk_bf16(float lo, float hi) { unsigned r; asm volatile("v_cvt_pk_bf16_f32 %0, %1, %2" : "=v"(r) : "v"(lo), "v"(hi)); return r; }
; __device__ __forceinline__ void cvt_matrix(const float* __restrict__ src, int K, int N, bf16_t* __restrict__ dst, int kind, int& base, float* lds_f, const int wv) {
;     ...
;         const int kt = t / nnb, nb = t % nnb, k0 = kt * 256, n0 = nb * 64;
;         int drow0 = n0, perm = 0;
;         if (kind == 1) { if (n0 < DFF) drow0 = 256 * (n0 >> 7) + (n0 & 127); else { const int n1 = n0 - DFF; drow0 = 256 * (n1 >> 7) + 128 + (n1 & 127); } }
;         if (kind == 2) perm = (n0 % 192) == 128;
;         { const int c4 = tid & 15, kr = tid >> 4;
;           f32x4 v[8];
; #pragma unroll
;           for (int i = 0; i < 8; ++i) v[i] = __builtin_nontemporal_load((const f32x4*)(src + (size_t)(k0 + kr + 32 * i) * N + n0 + 4 * c4));
; #pragma unroll
;           for (int i = 0; i < 8; ++i) { float* l = lds_f + (kr + 32 * i) * 65 + 4 * c4; l[0] = v[i][0]; l[1] = v[i][1]; l[2] = v[i][2]; l[3] = v[i][3]; } }
;         __syncthreads();
; #pragma unroll
;         for (int j = 0; j < 4; ++j) { const int idx = tid + 512 * j, r = ((idx >> 6) & 3) * 16 + ((idx >> 2) & 15), kc = (idx >> 8) * 4 + (idx & 3);
;             const int sc = perm ? ((r & 1) ? 32 + (r >> 1) : (r >> 1)) : r;
;             const float* l = lds_f + (kc * 8) * 65 + sc;
;             u32x4 w; w.x = cvt_pk_bf16(l[0], l[65]); w.y = cvt_pk_bf16(l[2 * 65], l[3 * 65]); w.z = cvt_pk_bf16(l[4 * 65], l[5 * 65]); w.w = cvt_pk_bf16(l[6 * 65], l[7 * 65]);
;             *(u32x4*)(dst + (size_t)(drow0 + r) * K + k0 + kc * 8) = w; }
;         __syncthreads();
.LBB0_70:
	s_andn2_b64 vcc, exec, s[28:29]
	s_cbranch_vccnz .LBB0_65
	s_add_i32 s26, s85, s86
	s_cmpk_gt_u32 s26, 0x2bf
	s_cbranch_scc1 .LBB0_65
	s_lshl_b32 s2, s26, 3
	s_and_b32 s2, s2, 0x1f00
	s_lshl_b32 s26, s26, 6
	s_and_b32 s86, s26, 0x7c0
	v_add_u32_e32 v26, s2, v18
	s_lshl_b32 s26, s86, 2
	v_ashrrev_i32_e32 v27, 31, v26
	v_lshl_add_u64 v[28:29], v[8:9], 0, s[26:27]
	v_lshlrev_b64 v[26:27], 13, v[26:27]
	v_lshl_add_u64 v[42:43], v[28:29], 0, v[26:27]
	v_add_co_u32_e32 v30, vcc, 0x40000, v42
	v_add_u32_e32 v6, v19, v21
	s_nop 0
	v_addc_co_u32_e32 v31, vcc, 0, v43, vcc
	v_add_co_u32_e32 v34, vcc, 0x80000, v42
	global_load_dwordx4 v[26:29], v[42:43], off nt
	s_nop 0
	global_load_dwordx4 v[30:33], v[30:31], off nt
	v_addc_co_u32_e32 v35, vcc, 0, v43, vcc
	v_add_co_u32_e32 v38, vcc, 0xc0000, v42
	v_add_u32_e32 v64, 0x4100, v6
	s_nop 0
	v_addc_co_u32_e32 v39, vcc, 0, v43, vcc
	v_add_co_u32_e32 v48, vcc, 0x100000, v42
	global_load_dwordx4 v[34:37], v[34:35], off nt
	s_nop 0
	global_load_dwordx4 v[38:41], v[38:39], off nt
	v_addc_co_u32_e32 v49, vcc, 0, v43, vcc
	v_add_co_u32_e32 v52, vcc, 0x140000, v42
	v_add_u32_e32 v65, 0x4108, v6
	s_nop 0
	v_addc_co_u32_e32 v53, vcc, 0, v43, vcc
	global_load_dwordx4 v[48:51], v[48:49], off nt
	s_nop 0
	global_load_dwordx4 v[52:55], v[52:53], off nt
	v_add_co_u32_e32 v56, vcc, 0x180000, v42
	v_add_u32_e32 v66, 0x6180, v6
	s_nop 0
	v_addc_co_u32_e32 v57, vcc, 0, v43, vcc
	global_load_dwordx4 v[56:59], v[56:57], off nt
	v_add_co_u32_e32 v42, vcc, 0x1c0000, v42
	v_add_u32_e32 v67, 0x6188, v6
	s_nop 0
	v_addc_co_u32_e32 v43, vcc, 0, v43, vcc
	global_load_dwordx4 v[60:63], v[42:43], off nt
	v_add_u32_e32 v42, 0x2080, v6
	v_add_u32_e32 v43, 0x2088, v6
	v_add_u32_e32 v68, 0x8200, v6
	v_add_u32_e32 v69, 0x8208, v6
	v_add_u32_e32 v70, 0xa280, v6
	v_add_u32_e32 v71, 0xa288, v6
	v_add_u32_e32 v72, 0xc300, v6
	v_add_u32_e32 v73, 0xc308, v6
	v_add_u32_e32 v74, 0xe380, v6
	v_add_u32_e32 v75, 0xe388, v6
	s_lshl_b32 s26, s2, 1
	s_waitcnt vmcnt(7)
	ds_write2_b32 v6, v26, v27 offset1:1
	ds_write2_b32 v6, v28, v29 offset0:2 offset1:3
	s_waitcnt vmcnt(6)
	ds_write2_b32 v42, v30, v31 offset1:1
	ds_write2_b32 v43, v32, v33 offset1:1
	s_waitcnt vmcnt(5)
	ds_write2_b32 v64, v34, v35 offset1:1
	ds_write2_b32 v65, v36, v37 offset1:1
	s_waitcnt vmcnt(4)
	ds_write2_b32 v66, v38, v39 offset1:1
	ds_write2_b32 v67, v40, v41 offset1:1
	s_waitcnt vmcnt(3)
	ds_write2_b32 v68, v48, v49 offset1:1
	ds_write2_b32 v69, v50, v51 offset1:1
	s_waitcnt vmcnt(2)
	ds_write2_b32 v70, v52, v53 offset1:1
	ds_write2_b32 v71, v54, v55 offset1:1
	s_waitcnt vmcnt(1)
	ds_write2_b32 v72, v56, v57 offset1:1
	ds_write2_b32 v73, v58, v59 offset1:1
	s_waitcnt vmcnt(0)
	ds_write2_b32 v74, v60, v61 offset1:1
	ds_write2_b32 v75, v62, v63 offset1:1
	s_waitcnt lgkmcnt(0)
	s_barrier
	ds_read2_b32 v[208:209], v22 offset1:65
	ds_read2_b32 v[210:211], v22 offset0:130 offset1:195
	v_add_u32_e32 v200, 0x400, v22
	ds_read2_b32 v[212:213], v200 offset0:4 offset1:69
	ds_read2_b32 v[214:215], v200 offset0:134 offset1:199
	ds_read2_b32 v[216:217], v23 offset1:65
	v_add_u32_e32 v201, 0x400, v23
	ds_read2_b32 v[218:219], v23 offset0:130 offset1:195
	ds_read2_b32 v[220:221], v201 offset0:4 offset1:69
	ds_read2_b32 v[222:223], v201 offset0:134 offset1:199
	s_waitcnt lgkmcnt(7)
	v_cvt_pk_bf16_f32 v26, v208, v209
	ds_read2_b32 v[224:225], v24 offset1:65
	s_waitcnt lgkmcnt(7)
	v_cvt_pk_bf16_f32 v27, v210, v211
	v_add_u32_e32 v202, 0x400, v24
	ds_read2_b32 v[226:227], v24 offset0:130 offset1:195
	s_waitcnt lgkmcnt(7)
	v_cvt_pk_bf16_f32 v28, v212, v213
	ds_read2_b32 v[228:229], v202 offset0:4 offset1:69
	v_or_b32_e32 v6, s86, v20
	v_mul_u32_u24_e32 v6, 0x1600, v6
	v_lshlrev_b32_e32 v6, 1, v6
	v_lshl_add_u64 v[32:33], s[66:67], 0, v[6:7]
	v_lshl_add_u64 v[32:33], v[32:33], 0, s[26:27]
	s_waitcnt lgkmcnt(7)
	v_cvt_pk_bf16_f32 v29, v214, v215
	ds_read2_b32 v[230:231], v202 offset0:134 offset1:199
	v_lshl_add_u64 v[34:35], v[10:11], 1, v[32:33]
	global_store_dwordx4 v[34:35], v[26:29], off
	s_nop 1
	v_lshl_add_u64 v[34:35], v[12:13], 1, v[32:33]
	s_waitcnt lgkmcnt(7)
	v_cvt_pk_bf16_f32 v26, v216, v217
	ds_read2_b32 v[232:233], v25 offset1:65
	s_waitcnt lgkmcnt(7)
	v_cvt_pk_bf16_f32 v27, v218, v219
	v_add_u32_e32 v203, 0x400, v25
	ds_read2_b32 v[234:235], v25 offset0:130 offset1:195
	s_waitcnt lgkmcnt(7)
	v_cvt_pk_bf16_f32 v28, v220, v221
	ds_read2_b32 v[236:237], v203 offset0:4 offset1:69
	s_waitcnt lgkmcnt(7)
	v_cvt_pk_bf16_f32 v29, v222, v223
	ds_read2_b32 v[238:239], v203 offset0:134 offset1:199
	global_store_dwordx4 v[34:35], v[26:29], off
	s_nop 1
	v_lshl_add_u64 v[34:35], v[14:15], 1, v[32:33]
	s_waitcnt lgkmcnt(7)
	v_cvt_pk_bf16_f32 v26, v224, v225
	s_waitcnt lgkmcnt(6)
	v_cvt_pk_bf16_f32 v27, v226, v227
	s_waitcnt lgkmcnt(5)
	v_cvt_pk_bf16_f32 v28, v228, v229
	s_waitcnt lgkmcnt(4)
	v_cvt_pk_bf16_f32 v29, v230, v231
	global_store_dwordx4 v[34:35], v[26:29], off
	s_nop 1
	v_lshl_add_u64 v[32:33], v[16:17], 1, v[32:33]
	s_waitcnt lgkmcnt(3)
	v_cvt_pk_bf16_f32 v26, v232, v233
	s_waitcnt lgkmcnt(2)
	v_cvt_pk_bf16_f32 v27, v234, v235
	s_waitcnt lgkmcnt(1)
	v_cvt_pk_bf16_f32 v28, v236, v237
	s_waitcnt lgkmcnt(0)
	v_cvt_pk_bf16_f32 v29, v238, v239
	global_store_dwordx4 v[32:33], v[26:29], off
	s_nop 1
	s_barrier
	s_branch .LBB0_65

; __device__ __forceinline__ unsigned cvt_pk_bf16(float lo, float hi) { unsigned r; asm volatile("v_cvt_pk_bf16_f32 %0, %1, %2" : "=v"(r) : "v"(lo), "v"(hi)); return r; }
; __device__ __forceinline__ void cvt_matrix(const float* __restrict__ src, int K, int N, bf16_t* __restrict__ dst, int kind, int& base, float* lds_f, const int wv) {
;     ...
;         const int g_ = q_ * PER + (sl_ < 3 ? b_ + G * sl_ : 3 * G + b_ - 32), t = g_ - base;
;         if (t < 0 || t >= ntiles) continue;
;         const int kt = t / nnb, nb = t % nnb, k0 = kt * 256, n0 = nb * 64;
;         int drow0 = n0, perm = 0;
;         if (kind == 1) { if (n0 < DFF) drow0 = 256 * (n0 >> 7) + (n0 & 127); else { const int n1 = n0 - DFF; drow0 = 256 * (n1 >> 7) + 128 + (n1 & 127); } }
;         if (kind == 2) perm = (n0 % 192) == 128;
;         { const int c4 = tid & 15, kr = tid >> 4;
;           f32x4 v[8];
; #pragma unroll
;           for (int i = 0; i < 8; ++i) v[i] = __builtin_nontemporal_load((const f32x4*)(src + (size_t)(k0 + kr + 32 * i) * N + n0 + 4 * c4));
; #pragma unroll
;           for (int i = 0; i < 8; ++i) { float* l = lds_f + (kr + 32 * i) * 65 + 4 * c4; l[0] = v[i][0]; l[1] = v[i][1]; l[2] = v[i][2]; l[3] = v[i][3]; } }
;         __syncthreads();
; #pragma unroll
;         for (int j = 0; j < 4; ++j) { const int idx = tid + 512 * j, r = ((idx >> 6) & 3) * 16 + ((idx >> 2) & 15), kc = (idx >> 8) * 4 + (idx & 3);
;             const int sc = perm ? ((r & 1) ? 32 + (r >> 1) : (r >> 1)) : r;
;             const float* l = lds_f + (kc * 8) * 65 + sc;
;             u32x4 w; w.x = cvt_pk_bf16(l[0], l[65]); w.y = cvt_pk_bf16(l[2 * 65], l[3 * 65]); w.z = cvt_pk_bf16(l[4 * 65], l[5 * 65]); w.w = cvt_pk_bf16(l[6 * 65], l[7 * 65]);
;             *(u32x4*)(dst + (size_t)(drow0 + r) * K + k0 + kc * 8) = w; }
;         __syncthreads();
.LBB0_78:
	s_cmpk_gt_u32 s65, 0x2bf
	s_cbranch_scc1 .LBB0_77
	s_and_b32 s2, s87, 0x1f00
	s_and_b32 s89, s88, 0x7c0
	v_add_u32_e32 v26, s2, v18
	s_lshl_b32 s26, s89, 2
	v_ashrrev_i32_e32 v27, 31, v26
	v_lshl_add_u64 v[28:29], v[8:9], 0, s[26:27]
	v_lshlrev_b64 v[26:27], 13, v[26:27]
	v_lshl_add_u64 v[42:43], v[28:29], 0, v[26:27]
	v_add_co_u32_e32 v30, vcc, 0x40000, v42
	v_add_u32_e32 v6, v19, v21
	s_nop 0
	v_addc_co_u32_e32 v31, vcc, 0, v43, vcc
	v_add_co_u32_e32 v34, vcc, 0x80000, v42
	global_load_dwordx4 v[26:29], v[42:43], off nt
	s_nop 0
	global_load_dwordx4 v[30:33], v[30:31], off nt
	v_addc_co_u32_e32 v35, vcc, 0, v43, vcc
	v_add_co_u32_e32 v38, vcc, 0xc0000, v42
	v_add_u32_e32 v64, 0x4100, v6
	s_nop 0
	v_addc_co_u32_e32 v39, vcc, 0, v43, vcc
	v_add_co_u32_e32 v48, vcc, 0x100000, v42
	global_load_dwordx4 v[34:37], v[34:35], off nt
	s_nop 0
	global_load_dwordx4 v[38:41], v[38:39], off nt
	v_addc_co_u32_e32 v49, vcc, 0, v43, vcc
	v_add_co_u32_e32 v52, vcc, 0x140000, v42
	v_add_u32_e32 v65, 0x4108, v6
	s_nop 0
	v_addc_co_u32_e32 v53, vcc, 0, v43, vcc
	global_load_dwordx4 v[48:51], v[48:49], off nt
	s_nop 0
	global_load_dwordx4 v[52:55], v[52:53], off nt
	v_add_co_u32_e32 v56, vcc, 0x180000, v42
	v_add_u32_e32 v66, 0x6180, v6
	s_nop 0
	v_addc_co_u32_e32 v57, vcc, 0, v43, vcc
	global_load_dwordx4 v[56:59], v[56:57], off nt
	v_add_co_u32_e32 v42, vcc, 0x1c0000, v42
	v_add_u32_e32 v67, 0x6188, v6
	s_nop 0
	v_addc_co_u32_e32 v43, vcc, 0, v43, vcc
	global_load_dwordx4 v[60:63], v[42:43], off nt
	v_add_u32_e32 v42, 0x2080, v6
	v_add_u32_e32 v43, 0x2088, v6
	v_add_u32_e32 v68, 0x8200, v6
	v_add_u32_e32 v69, 0x8208, v6
	v_add_u32_e32 v70, 0xa280, v6
	v_add_u32_e32 v71, 0xa288, v6
	v_add_u32_e32 v72, 0xc300, v6
	v_add_u32_e32 v73, 0xc308, v6
	v_add_u32_e32 v74, 0xe380, v6
	v_add_u32_e32 v75, 0xe388, v6
	s_lshl_b32 s26, s2, 1
	s_waitcnt vmcnt(7)
	ds_write2_b32 v6, v26, v27 offset1:1
	ds_write2_b32 v6, v28, v29 offset0:2 offset1:3
	s_waitcnt vmcnt(6)
	ds_write2_b32 v42, v30, v31 offset1:1
	ds_write2_b32 v43, v32, v33 offset1:1
	s_waitcnt vmcnt(5)
	ds_write2_b32 v64, v34, v35 offset1:1
	ds_write2_b32 v65, v36, v37 offset1:1
	s_waitcnt vmcnt(4)
	ds_write2_b32 v66, v38, v39 offset1:1
	ds_write2_b32 v67, v40, v41 offset1:1
	s_waitcnt vmcnt(3)
	ds_write2_b32 v68, v48, v49 offset1:1
	ds_write2_b32 v69, v50, v51 offset1:1
	s_waitcnt vmcnt(2)
	ds_write2_b32 v70, v52, v53 offset1:1
	ds_write2_b32 v71, v54, v55 offset1:1
	s_waitcnt vmcnt(1)
	ds_write2_b32 v72, v56, v57 offset1:1
	ds_write2_b32 v73, v58, v59 offset1:1
	s_waitcnt vmcnt(0)
	ds_write2_b32 v74, v60, v61 offset1:1
	ds_write2_b32 v75, v62, v63 offset1:1
	s_waitcnt lgkmcnt(0)
	s_barrier
	ds_read2_b32 v[208:209], v22 offset1:65
	ds_read2_b32 v[210:211], v22 offset0:130 offset1:195
	v_add_u32_e32 v200, 0x400, v22
	ds_read2_b32 v[212:213], v200 offset0:4 offset1:69
	ds_read2_b32 v[214:215], v200 offset0:134 offset1:199
	ds_read2_b32 v[216:217], v23 offset1:65
	v_add_u32_e32 v201, 0x400, v23
	ds_read2_b32 v[218:219], v23 offset0:130 offset1:195
	ds_read2_b32 v[220:221], v201 offset0:4 offset1:69
	ds_read2_b32 v[222:223], v201 offset0:134 offset1:199
	s_waitcnt lgkmcnt(7)
	v_cvt_pk_bf16_f32 v26, v208, v209
	ds_read2_b32 v[224:225], v24 offset1:65
	s_waitcnt lgkmcnt(7)
	v_cvt_pk_bf16_f32 v27, v210, v211
	v_add_u32_e32 v202, 0x400, v24
	ds_read2_b32 v[226:227], v24 offset0:130 offset1:195
	s_waitcnt lgkmcnt(7)
	v_cvt_pk_bf16_f32 v28, v212, v213
	ds_read2_b32 v[228:229], v202 offset0:4 offset1:69
	v_or_b32_e32 v6, s89, v20
	v_mul_u32_u24_e32 v6, 0x1600, v6
	v_lshlrev_b32_e32 v6, 1, v6
	v_lshl_add_u64 v[32:33], s[66:67], 0, v[6:7]
	v_lshl_add_u64 v[32:33], v[32:33], 0, s[26:27]
	s_waitcnt lgkmcnt(7)
	v_cvt_pk_bf16_f32 v29, v214, v215
	ds_read2_b32 v[230:231], v202 offset0:134 offset1:199
	v_lshl_add_u64 v[34:35], v[10:11], 1, v[32:33]
	global_store_dwordx4 v[34:35], v[26:29], off
	s_nop 1
	v_lshl_add_u64 v[34:35], v[12:13], 1, v[32:33]
	s_waitcnt lgkmcnt(7)
	v_cvt_pk_bf16_f32 v26, v216, v217
	ds_read2_b32 v[232:233], v25 offset1:65
	s_waitcnt lgkmcnt(7)
	v_cvt_pk_bf16_f32 v27, v218, v219
	v_add_u32_e32 v203, 0x400, v25
	ds_read2_b32 v[234:235], v25 offset0:130 offset1:195
	s_waitcnt lgkmcnt(7)
	v_cvt_pk_bf16_f32 v28, v220, v221
	ds_read2_b32 v[236:237], v203 offset0:4 offset1:69
	s_waitcnt lgkmcnt(7)
	v_cvt_pk_bf16_f32 v29, v222, v223
	ds_read2_b32 v[238:239], v203 offset0:134 offset1:199
	global_store_dwordx4 v[34:35], v[26:29], off
	s_nop 1
	v_lshl_add_u64 v[34:35], v[14:15], 1, v[32:33]
	s_waitcnt lgkmcnt(7)
	v_cvt_pk_bf16_f32 v26, v224, v225
	s_waitcnt lgkmcnt(6)
	v_cvt_pk_bf16_f32 v27, v226, v227
	s_waitcnt lgkmcnt(5)
	v_cvt_pk_bf16_f32 v28, v228, v229
	s_waitcnt lgkmcnt(4)
	v_cvt_pk_bf16_f32 v29, v230, v231
	global_store_dwordx4 v[34:35], v[26:29], off
	s_nop 1
	v_lshl_add_u64 v[32:33], v[16:17], 1, v[32:33]
	s_waitcnt lgkmcnt(3)
	v_cvt_pk_bf16_f32 v26, v232, v233
	s_waitcnt lgkmcnt(2)
	v_cvt_pk_bf16_f32 v27, v234, v235
	s_waitcnt lgkmcnt(1)
	v_cvt_pk_bf16_f32 v28, v236, v237
	s_waitcnt lgkmcnt(0)
	v_cvt_pk_bf16_f32 v29, v238, v239
	global_store_dwordx4 v[32:33], v[26:29], off
	s_nop 1
	s_barrier
	s_branch .LBB0_77
; __device__ __forceinline__ unsigned cvt_pk_bf16(float lo, float hi) { unsigned r; asm volatile("v_cvt_pk_bf16_f32 %0, %1, %2" : "=v"(r) : "v"(lo), "v"(hi)); return r; }
; __device__ __forceinline__ void cvt_matrix(const float* __restrict__ src, int K, int N, bf16_t* __restrict__ dst, int kind, int& base, float* lds_f, const int wv) {
;     ...
;         const int g_ = q_ * PER + (sl_ < 3 ? b_ + G * sl_ : 3 * G + b_ - 32), t = g_ - base;
;         if (t < 0 || t >= ntiles) continue;
;         const int kt = t / nnb, nb = t % nnb, k0 = kt * 256, n0 = nb * 64;
;         int drow0 = n0, perm = 0;
;         if (kind == 1) { if (n0 < DFF) drow0 = 256 * (n0 >> 7) + (n0 & 127); else { const int n1 = n0 - DFF; drow0 = 256 * (n1 >> 7) + 128 + (n1 & 127); } }
;         if (kind == 2) perm = (n0 % 192) == 128;
;         { const int c4 = tid & 15, kr = tid >> 4;
;           f32x4 v[8];
; #pragma unroll
;           for (int i = 0; i < 8; ++i) v[i] = __builtin_nontemporal_load((const f32x4*)(src + (size_t)(k0 + kr + 32 * i) * N + n0 + 4 * c4));
; #pragma unroll
;           for (int i = 0; i < 8; ++i) { float* l = lds_f + (kr + 32 * i) * 65 + 4 * c4; l[0] = v[i][0]; l[1] = v[i][1]; l[2] = v[i][2]; l[3] = v[i][3]; } }
;         __syncthreads();
; #pragma unroll
;         for (int j = 0; j < 4; ++j) { const int idx = tid + 512 * j, r = ((idx >> 6) & 3) * 16 + ((idx >> 2) & 15), kc = (idx >> 8) * 4 + (idx & 3);
;             const int sc = perm ? ((r & 1) ? 32 + (r >> 1) : (r >> 1)) : r;
;             const float* l = lds_f + (kc * 8) * 65 + sc;
;             u32x4 w; w.x = cvt_pk_bf16(l[0], l[65]); w.y = cvt_pk_bf16(l[2 * 65], l[3 * 65]); w.z = cvt_pk_bf16(l[4 * 65], l[5 * 65]); w.w = cvt_pk_bf16(l[6 * 65], l[7 * 65]);
;             *(u32x4*)(dst + (size_t)(drow0 + r) * K + k0 + kc * 8) = w; }
;         __syncthreads();
.LBB0_80:
	s_andn2_b64 vcc, exec, s[28:29]
	s_cbranch_vccnz .LBB0_75
	s_add_i32 s26, s64, s85
	s_cmpk_gt_u32 s26, 0x2bf
	s_cbranch_scc1 .LBB0_75
	s_lshl_b32 s2, s26, 3
	s_and_b32 s2, s2, 0x1f00
	s_lshl_b32 s26, s26, 6
	s_and_b32 s65, s26, 0x7c0
	v_add_u32_e32 v26, s2, v18
	s_lshl_b32 s26, s65, 2
	v_ashrrev_i32_e32 v27, 31, v26
	v_lshl_add_u64 v[28:29], v[8:9], 0, s[26:27]
	v_lshlrev_b64 v[26:27], 13, v[26:27]
	v_lshl_add_u64 v[42:43], v[28:29], 0, v[26:27]
	v_add_co_u32_e32 v30, vcc, 0x40000, v42
	v_add_u32_e32 v6, v19, v21
	s_nop 0
	v_addc_co_u32_e32 v31, vcc, 0, v43, vcc
	v_add_co_u32_e32 v34, vcc, 0x80000, v42
	global_load_dwordx4 v[26:29], v[42:43], off nt
	s_nop 0
	global_load_dwordx4 v[30:33], v[30:31], off nt
	v_addc_co_u32_e32 v35, vcc, 0, v43, vcc
	v_add_co_u32_e32 v38, vcc, 0xc0000, v42
	v_add_u32_e32 v64, 0x4100, v6
	s_nop 0
	v_addc_co_u32_e32 v39, vcc, 0, v43, vcc
	v_add_co_u32_e32 v48, vcc, 0x100000, v42
	global_load_dwordx4 v[34:37], v[34:35], off nt
	s_nop 0
	global_load_dwordx4 v[38:41], v[38:39], off nt
	v_addc_co_u32_e32 v49, vcc, 0, v43, vcc
	v_add_co_u32_e32 v52, vcc, 0x140000, v42
	v_add_u32_e32 v65, 0x4108, v6
	s_nop 0
	v_addc_co_u32_e32 v53, vcc, 0, v43, vcc
	global_load_dwordx4 v[48:51], v[48:49], off nt
	s_nop 0
	global_load_dwordx4 v[52:55], v[52:53], off nt
	v_add_co_u32_e32 v56, vcc, 0x180000, v42
	v_add_u32_e32 v66, 0x6180, v6
	s_nop 0
	v_addc_co_u32_e32 v57, vcc, 0, v43, vcc
	global_load_dwordx4 v[56:59], v[56:57], off nt
	v_add_co_u32_e32 v42, vcc, 0x1c0000, v42
	v_add_u32_e32 v67, 0x6188, v6
	s_nop 0
	v_addc_co_u32_e32 v43, vcc, 0, v43, vcc
	global_load_dwordx4 v[60:63], v[42:43], off nt
	v_add_u32_e32 v42, 0x2080, v6
	v_add_u32_e32 v43, 0x2088, v6
	v_add_u32_e32 v68, 0x8200, v6
	v_add_u32_e32 v69, 0x8208, v6
	v_add_u32_e32 v70, 0xa280, v6
	v_add_u32_e32 v71, 0xa288, v6
	v_add_u32_e32 v72, 0xc300, v6
	v_add_u32_e32 v73, 0xc308, v6
	v_add_u32_e32 v74, 0xe380, v6
	v_add_u32_e32 v75, 0xe388, v6
	s_lshl_b32 s26, s2, 1
	s_waitcnt vmcnt(7)
	ds_write2_b32 v6, v26, v27 offset1:1
	ds_write2_b32 v6, v28, v29 offset0:2 offset1:3
	s_waitcnt vmcnt(6)
	ds_write2_b32 v42, v30, v31 offset1:1
	ds_write2_b32 v43, v32, v33 offset1:1
	s_waitcnt vmcnt(5)
	ds_write2_b32 v64, v34, v35 offset1:1
	ds_write2_b32 v65, v36, v37 offset1:1
	s_waitcnt vmcnt(4)
	ds_write2_b32 v66, v38, v39 offset1:1
	ds_write2_b32 v67, v40, v41 offset1:1
	s_waitcnt vmcnt(3)
	ds_write2_b32 v68, v48, v49 offset1:1
	ds_write2_b32 v69, v50, v51 offset1:1
	s_waitcnt vmcnt(2)
	ds_write2_b32 v70, v52, v53 offset1:1
	ds_write2_b32 v71, v54, v55 offset1:1
	s_waitcnt vmcnt(1)
	ds_write2_b32 v72, v56, v57 offset1:1
	ds_write2_b32 v73, v58, v59 offset1:1
	s_waitcnt vmcnt(0)
	ds_write2_b32 v74, v60, v61 offset1:1
	ds_write2_b32 v75, v62, v63 offset1:1
	s_waitcnt lgkmcnt(0)
	s_barrier
	ds_read2_b32 v[208:209], v22 offset1:65
	ds_read2_b32 v[210:211], v22 offset0:130 offset1:195
	v_add_u32_e32 v200, 0x400, v22
	ds_read2_b32 v[212:213], v200 offset0:4 offset1:69
	ds_read2_b32 v[214:215], v200 offset0:134 offset1:199
	ds_read2_b32 v[216:217], v23 offset1:65
	v_add_u32_e32 v201, 0x400, v23
	ds_read2_b32 v[218:219], v23 offset0:130 offset1:195
	ds_read2_b32 v[220:221], v201 offset0:4 offset1:69
	ds_read2_b32 v[222:223], v201 offset0:134 offset1:199
	s_waitcnt lgkmcnt(7)
	v_cvt_pk_bf16_f32 v26, v208, v209
	ds_read2_b32 v[224:225], v24 offset1:65
	s_waitcnt lgkmcnt(7)
	v_cvt_pk_bf16_f32 v27, v210, v211
	v_add_u32_e32 v202, 0x400, v24
	ds_read2_b32 v[226:227], v24 offset0:130 offset1:195
	s_waitcnt lgkmcnt(7)
	v_cvt_pk_bf16_f32 v28, v212, v213
	ds_read2_b32 v[228:229], v202 offset0:4 offset1:69
	v_or_b32_e32 v6, s65, v20
	v_mul_u32_u24_e32 v6, 0x1600, v6
	v_lshlrev_b32_e32 v6, 1, v6
	v_lshl_add_u64 v[32:33], s[66:67], 0, v[6:7]
	v_lshl_add_u64 v[32:33], v[32:33], 0, s[26:27]
	s_waitcnt lgkmcnt(7)
	v_cvt_pk_bf16_f32 v29, v214, v215
	ds_read2_b32 v[230:231], v202 offset0:134 offset1:199
	v_lshl_add_u64 v[34:35], v[10:11], 1, v[32:33]
	global_store_dwordx4 v[34:35], v[26:29], off
	s_nop 1
	v_lshl_add_u64 v[34:35], v[12:13], 1, v[32:33]
	s_waitcnt lgkmcnt(7)
	v_cvt_pk_bf16_f32 v26, v216, v217
	ds_read2_b32 v[232:233], v25 offset1:65
	s_waitcnt lgkmcnt(7)
	v_cvt_pk_bf16_f32 v27, v218, v219
	v_add_u32_e32 v203, 0x400, v25
	ds_read2_b32 v[234:235], v25 offset0:130 offset1:195
	s_waitcnt lgkmcnt(7)
	v_cvt_pk_bf16_f32 v28, v220, v221
	ds_read2_b32 v[236:237], v203 offset0:4 offset1:69
	s_waitcnt lgkmcnt(7)
	v_cvt_pk_bf16_f32 v29, v222, v223
	ds_read2_b32 v[238:239], v203 offset0:134 offset1:199
	global_store_dwordx4 v[34:35], v[26:29], off
	s_nop 1
	v_lshl_add_u64 v[34:35], v[14:15], 1, v[32:33]
	s_waitcnt lgkmcnt(7)
	v_cvt_pk_bf16_f32 v26, v224, v225
	s_waitcnt lgkmcnt(6)
	v_cvt_pk_bf16_f32 v27, v226, v227
	s_waitcnt lgkmcnt(5)
	v_cvt_pk_bf16_f32 v28, v228, v229
	s_waitcnt lgkmcnt(4)
	v_cvt_pk_bf16_f32 v29, v230, v231
	global_store_dwordx4 v[34:35], v[26:29], off
	s_nop 1
	v_lshl_add_u64 v[32:33], v[16:17], 1, v[32:33]
	s_waitcnt lgkmcnt(3)
	v_cvt_pk_bf16_f32 v26, v232, v233
	s_waitcnt lgkmcnt(2)
	v_cvt_pk_bf16_f32 v27, v234, v235
	s_waitcnt lgkmcnt(1)
	v_cvt_pk_bf16_f32 v28, v236, v237
	s_waitcnt lgkmcnt(0)
	v_cvt_pk_bf16_f32 v29, v238, v239
	global_store_dwordx4 v[32:33], v[26:29], off
	s_nop 1
	s_barrier
	s_branch .LBB0_75

; __device__ __forceinline__ unsigned cvt_pk_bf16(float lo, float hi) { unsigned r; asm volatile("v_cvt_pk_bf16_f32 %0, %1, %2" : "=v"(r) : "v"(lo), "v"(hi)); return r; }
; __device__ __forceinline__ void cvt_matrix(const float* __restrict__ src, int K, int N, bf16_t* __restrict__ dst, int kind, int& base, float* lds_f, const int wv) {
;     ...
;         const int g_ = q_ * PER + (sl_ < 3 ? b_ + G * sl_ : 3 * G + b_ - 32), t = g_ - base;
;         if (t < 0 || t >= ntiles) continue;
;         const int kt = t / nnb, nb = t % nnb, k0 = kt * 256, n0 = nb * 64;
;         int drow0 = n0, perm = 0;
;         if (kind == 1) { if (n0 < DFF) drow0 = 256 * (n0 >> 7) + (n0 & 127); else { const int n1 = n0 - DFF; drow0 = 256 * (n1 >> 7) + 128 + (n1 & 127); } }
;         if (kind == 2) perm = (n0 % 192) == 128;
;         { const int c4 = tid & 15, kr = tid >> 4;
;           f32x4 v[8];
; #pragma unroll
;           for (int i = 0; i < 8; ++i) v[i] = __builtin_nontemporal_load((const f32x4*)(src + (size_t)(k0 + kr + 32 * i) * N + n0 + 4 * c4));
; #pragma unroll
;           for (int i = 0; i < 8; ++i) { float* l = lds_f + (kr + 32 * i) * 65 + 4 * c4; l[0] = v[i][0]; l[1] = v[i][1]; l[2] = v[i][2]; l[3] = v[i][3]; } }
;         __syncthreads();
; #pragma unroll
;         for (int j = 0; j < 4; ++j) { const int idx = tid + 512 * j, r = ((idx >> 6) & 3) * 16 + ((idx >> 2) & 15), kc = (idx >> 8) * 4 + (idx & 3);
;             const int sc = perm ? ((r & 1) ? 32 + (r >> 1) : (r >> 1)) : r;
;             const float* l = lds_f + (kc * 8) * 65 + sc;
;             u32x4 w; w.x = cvt_pk_bf16(l[0], l[65]); w.y = cvt_pk_bf16(l[2 * 65], l[3 * 65]); w.z = cvt_pk_bf16(l[4 * 65], l[5 * 65]); w.w = cvt_pk_bf16(l[6 * 65], l[7 * 65]);
;             *(u32x4*)(dst + (size_t)(drow0 + r) * K + k0 + kc * 8) = w; }
;         __syncthreads();
.LBB0_88:
	s_cmpk_gt_u32 s86, 0x167
	s_cbranch_scc1 .LBB0_87
	s_and_b32 s2, s86, 0xffff
	s_mulk_i32 s2, 0x2d83
	s_lshr_b32 s26, s2, 19
	s_mul_i32 s26, s26, 45
	s_sub_i32 s26, s86, s26
	s_lshr_b32 s2, s2, 11
	s_lshl_b32 s26, s26, 6
	s_and_b32 s2, s2, 0xff00
	s_and_b32 s90, s26, 0xffc0
	v_add_u32_e32 v6, s2, v18
	s_lshl_b32 s26, s90, 2
	v_lshl_add_u64 v[42:43], v[8:9], 0, s[26:27]
	v_add_u32_e32 v28, 32, v6
	v_add_u32_e32 v34, 64, v6
	v_add_u32_e32 v36, 0x60, v6
	v_add_u32_e32 v48, 0x80, v6
	v_add_u32_e32 v50, 0xa0, v6
	v_mad_i64_i32 v[26:27], s[88:89], v6, s80, v[42:43]
	v_mad_i64_i32 v[30:31], s[88:89], v28, s80, v[42:43]
	v_mad_i64_i32 v[34:35], s[88:89], v34, s80, v[42:43]
	v_mad_i64_i32 v[38:39], s[88:89], v36, s80, v[42:43]
	v_mad_i64_i32 v[48:49], s[88:89], v48, s80, v[42:43]
	v_mad_i64_i32 v[52:53], s[88:89], v50, s80, v[42:43]
	global_load_dwordx4 v[26:29], v[26:27], off nt
	s_nop 0
	global_load_dwordx4 v[30:33], v[30:31], off nt
	s_nop 0
	global_load_dwordx4 v[34:37], v[34:35], off nt
	s_nop 0
	global_load_dwordx4 v[38:41], v[38:39], off nt
	s_nop 0
	global_load_dwordx4 v[48:51], v[48:49], off nt
	s_nop 0
	global_load_dwordx4 v[52:55], v[52:53], off nt
	v_add_u32_e32 v56, 0xc0, v6
	v_mad_i64_i32 v[56:57], s[88:89], v56, s80, v[42:43]
	global_load_dwordx4 v[56:59], v[56:57], off nt
	v_add_u32_e32 v6, 0xe0, v6
	v_mad_i64_i32 v[42:43], s[88:89], v6, s80, v[42:43]
	global_load_dwordx4 v[60:63], v[42:43], off nt
	v_add_u32_e32 v6, v19, v21
	v_add_u32_e32 v42, 0x2080, v6
	v_add_u32_e32 v43, 0x2088, v6
	v_add_u32_e32 v64, 0x4100, v6
	v_add_u32_e32 v65, 0x4108, v6
	v_add_u32_e32 v66, 0x6180, v6
	v_add_u32_e32 v67, 0x6188, v6
	v_add_u32_e32 v68, 0x8200, v6
	v_add_u32_e32 v69, 0x8208, v6
	v_add_u32_e32 v70, 0xa280, v6
	v_add_u32_e32 v71, 0xa288, v6
	v_add_u32_e32 v72, 0xc300, v6
	v_add_u32_e32 v73, 0xc308, v6
	v_add_u32_e32 v74, 0xe380, v6
	v_add_u32_e32 v75, 0xe388, v6
	s_lshl_b32 s26, s2, 1
	s_waitcnt vmcnt(7)
	ds_write2_b32 v6, v26, v27 offset1:1
	ds_write2_b32 v6, v28, v29 offset0:2 offset1:3
	s_waitcnt vmcnt(6)
	ds_write2_b32 v42, v30, v31 offset1:1
	ds_write2_b32 v43, v32, v33 offset1:1
	s_waitcnt vmcnt(5)
	ds_write2_b32 v64, v34, v35 offset1:1
	ds_write2_b32 v65, v36, v37 offset1:1
	s_waitcnt vmcnt(4)
	ds_write2_b32 v66, v38, v39 offset1:1
	ds_write2_b32 v67, v40, v41 offset1:1
	s_waitcnt vmcnt(3)
	ds_write2_b32 v68, v48, v49 offset1:1
	ds_write2_b32 v69, v50, v51 offset1:1
	s_waitcnt vmcnt(2)
	ds_write2_b32 v70, v52, v53 offset1:1
	ds_write2_b32 v71, v54, v55 offset1:1
	s_waitcnt vmcnt(1)
	ds_write2_b32 v72, v56, v57 offset1:1
	ds_write2_b32 v73, v58, v59 offset1:1
	s_waitcnt vmcnt(0)
	ds_write2_b32 v74, v60, v61 offset1:1
	ds_write2_b32 v75, v62, v63 offset1:1
	s_waitcnt lgkmcnt(0)
	s_barrier
	ds_read2_b32 v[208:209], v22 offset1:65
	ds_read2_b32 v[210:211], v22 offset0:130 offset1:195
	v_add_u32_e32 v200, 0x400, v22
	ds_read2_b32 v[212:213], v200 offset0:4 offset1:69
	ds_read2_b32 v[214:215], v200 offset0:134 offset1:199
	ds_read2_b32 v[216:217], v23 offset1:65
	v_add_u32_e32 v201, 0x400, v23
	ds_read2_b32 v[218:219], v23 offset0:130 offset1:195
	ds_read2_b32 v[220:221], v201 offset0:4 offset1:69
	ds_read2_b32 v[222:223], v201 offset0:134 offset1:199
	s_waitcnt lgkmcnt(7)
	v_cvt_pk_bf16_f32 v26, v208, v209
	ds_read2_b32 v[224:225], v24 offset1:65
	s_waitcnt lgkmcnt(7)
	v_cvt_pk_bf16_f32 v27, v210, v211
	v_add_u32_e32 v202, 0x400, v24
	ds_read2_b32 v[226:227], v24 offset0:130 offset1:195
	s_waitcnt lgkmcnt(7)
	v_cvt_pk_bf16_f32 v28, v212, v213
	ds_read2_b32 v[228:229], v202 offset0:4 offset1:69
	v_or_b32_e32 v6, s90, v20
	v_lshlrev_b32_e32 v6, 12, v6
	v_lshl_add_u64 v[32:33], s[64:65], 0, v[6:7]
	v_lshl_add_u64 v[32:33], v[32:33], 0, s[26:27]
	s_waitcnt lgkmcnt(7)
	v_cvt_pk_bf16_f32 v29, v214, v215
	ds_read2_b32 v[230:231], v202 offset0:134 offset1:199
	v_lshl_add_u64 v[34:35], v[10:11], 1, v[32:33]
	global_store_dwordx4 v[34:35], v[26:29], off
	s_nop 1
	v_lshl_add_u64 v[34:35], v[12:13], 1, v[32:33]
	s_waitcnt lgkmcnt(7)
	v_cvt_pk_bf16_f32 v26, v216, v217
	ds_read2_b32 v[232:233], v25 offset1:65
	s_waitcnt lgkmcnt(7)
	v_cvt_pk_bf16_f32 v27, v218, v219
	v_add_u32_e32 v203, 0x400, v25
	ds_read2_b32 v[234:235], v25 offset0:130 offset1:195
	s_waitcnt lgkmcnt(7)
	v_cvt_pk_bf16_f32 v28, v220, v221
	ds_read2_b32 v[236:237], v203 offset0:4 offset1:69
	s_waitcnt lgkmcnt(7)
	v_cvt_pk_bf16_f32 v29, v222, v223
	ds_read2_b32 v[238:239], v203 offset0:134 offset1:199
	global_store_dwordx4 v[34:35], v[26:29], off
	s_nop 1
	v_lshl_add_u64 v[34:35], v[14:15], 1, v[32:33]
	s_waitcnt lgkmcnt(7)
	v_cvt_pk_bf16_f32 v26, v224, v225
	s_waitcnt lgkmcnt(6)
	v_cvt_pk_bf16_f32 v27, v226, v227
	s_waitcnt lgkmcnt(5)
	v_cvt_pk_bf16_f32 v28, v228, v229
	s_waitcnt lgkmcnt(4)
	v_cvt_pk_bf16_f32 v29, v230, v231
	global_store_dwordx4 v[34:35], v[26:29], off
	s_nop 1
	v_lshl_add_u64 v[32:33], v[16:17], 1, v[32:33]
	s_waitcnt lgkmcnt(3)
	v_cvt_pk_bf16_f32 v26, v232, v233
	s_waitcnt lgkmcnt(2)
	v_cvt_pk_bf16_f32 v27, v234, v235
	s_waitcnt lgkmcnt(1)
	v_cvt_pk_bf16_f32 v28, v236, v237
	s_waitcnt lgkmcnt(0)
	v_cvt_pk_bf16_f32 v29, v238, v239
	global_store_dwordx4 v[32:33], v[26:29], off
	s_nop 1
	s_barrier
	s_branch .LBB0_87
; __device__ __forceinline__ unsigned cvt_pk_bf16(float lo, float hi) { unsigned r; asm volatile("v_cvt_pk_bf16_f32 %0, %1, %2" : "=v"(r) : "v"(lo), "v"(hi)); return r; }
; __device__ __forceinline__ void cvt_matrix(const float* __restrict__ src, int K, int N, bf16_t* __restrict__ dst, int kind, int& base, float* lds_f, const int wv) {
;     ...
;         const int g_ = q_ * PER + (sl_ < 3 ? b_ + G * sl_ : 3 * G + b_ - 32), t = g_ - base;
;         if (t < 0 || t >= ntiles) continue;
;         const int kt = t / nnb, nb = t % nnb, k0 = kt * 256, n0 = nb * 64;
;         int drow0 = n0, perm = 0;
;         if (kind == 1) { if (n0 < DFF) drow0 = 256 * (n0 >> 7) + (n0 & 127); else { const int n1 = n0 - DFF; drow0 = 256 * (n1 >> 7) + 128 + (n1 & 127); } }
;         if (kind == 2) perm = (n0 % 192) == 128;
;         { const int c4 = tid & 15, kr = tid >> 4;
;           f32x4 v[8];
; #pragma unroll
;           for (int i = 0; i < 8; ++i) v[i] = __builtin_nontemporal_load((const f32x4*)(src + (size_t)(k0 + kr + 32 * i) * N + n0 + 4 * c4));
; #pragma unroll
;           for (int i = 0; i < 8; ++i) { float* l = lds_f + (kr + 32 * i) * 65 + 4 * c4; l[0] = v[i][0]; l[1] = v[i][1]; l[2] = v[i][2]; l[3] = v[i][3]; } }
;         __syncthreads();
; #pragma unroll
;         for (int j = 0; j < 4; ++j) { const int idx = tid + 512 * j, r = ((idx >> 6) & 3) * 16 + ((idx >> 2) & 15), kc = (idx >> 8) * 4 + (idx & 3);
;             const int sc = perm ? ((r & 1) ? 32 + (r >> 1) : (r >> 1)) : r;
;             const float* l = lds_f + (kc * 8) * 65 + sc;
;             u32x4 w; w.x = cvt_pk_bf16(l[0], l[65]); w.y = cvt_pk_bf16(l[2 * 65], l[3 * 65]); w.z = cvt_pk_bf16(l[4 * 65], l[5 * 65]); w.w = cvt_pk_bf16(l[6 * 65], l[7 * 65]);
;             *(u32x4*)(dst + (size_t)(drow0 + r) * K + k0 + kc * 8) = w; }
;         __syncthreads();
.LBB0_90:
	s_andn2_b64 vcc, exec, s[28:29]
	s_cbranch_vccnz .LBB0_85
	s_add_i32 s26, s77, s85
	s_cmpk_gt_u32 s26, 0x167
	s_cbranch_scc1 .LBB0_85
	s_and_b32 s2, s26, 0xffff
	s_mulk_i32 s2, 0x2d83
	s_lshr_b32 s85, s2, 19
	s_mul_i32 s85, s85, 45
	s_sub_i32 s26, s26, s85
	s_lshr_b32 s2, s2, 11
	s_lshl_b32 s26, s26, 6
	s_and_b32 s2, s2, 0xff00
	s_and_b32 s85, s26, 0xffc0
	v_add_u32_e32 v6, s2, v18
	s_lshl_b32 s26, s85, 2
	v_lshl_add_u64 v[42:43], v[8:9], 0, s[26:27]
	v_add_u32_e32 v28, 32, v6
	v_add_u32_e32 v34, 64, v6
	v_add_u32_e32 v36, 0x60, v6
	v_add_u32_e32 v48, 0x80, v6
	v_add_u32_e32 v50, 0xa0, v6
	v_mad_i64_i32 v[26:27], s[86:87], v6, s80, v[42:43]
	v_mad_i64_i32 v[30:31], s[86:87], v28, s80, v[42:43]
	v_mad_i64_i32 v[34:35], s[86:87], v34, s80, v[42:43]
	v_mad_i64_i32 v[38:39], s[86:87], v36, s80, v[42:43]
	v_mad_i64_i32 v[48:49], s[86:87], v48, s80, v[42:43]
	v_mad_i64_i32 v[52:53], s[86:87], v50, s80, v[42:43]
	global_load_dwordx4 v[26:29], v[26:27], off nt
	s_nop 0
	global_load_dwordx4 v[30:33], v[30:31], off nt
	s_nop 0
	global_load_dwordx4 v[34:37], v[34:35], off nt
	s_nop 0
	global_load_dwordx4 v[38:41], v[38:39], off nt
	s_nop 0
	global_load_dwordx4 v[48:51], v[48:49], off nt
	s_nop 0
	global_load_dwordx4 v[52:55], v[52:53], off nt
	v_add_u32_e32 v56, 0xc0, v6
	v_mad_i64_i32 v[56:57], s[86:87], v56, s80, v[42:43]
	global_load_dwordx4 v[56:59], v[56:57], off nt
	v_add_u32_e32 v6, 0xe0, v6
	v_mad_i64_i32 v[42:43], s[86:87], v6, s80, v[42:43]
	global_load_dwordx4 v[60:63], v[42:43], off nt
	v_add_u32_e32 v6, v19, v21
	v_add_u32_e32 v42, 0x2080, v6
	v_add_u32_e32 v43, 0x2088, v6
	v_add_u32_e32 v64, 0x4100, v6
	v_add_u32_e32 v65, 0x4108, v6
	v_add_u32_e32 v66, 0x6180, v6
	v_add_u32_e32 v67, 0x6188, v6
	v_add_u32_e32 v68, 0x8200, v6
	v_add_u32_e32 v69, 0x8208, v6
	v_add_u32_e32 v70, 0xa280, v6
	v_add_u32_e32 v71, 0xa288, v6
	v_add_u32_e32 v72, 0xc300, v6
	v_add_u32_e32 v73, 0xc308, v6
	v_add_u32_e32 v74, 0xe380, v6
	v_add_u32_e32 v75, 0xe388, v6
	s_lshl_b32 s26, s2, 1
	s_waitcnt vmcnt(7)
	ds_write2_b32 v6, v26, v27 offset1:1
	ds_write2_b32 v6, v28, v29 offset0:2 offset1:3
	s_waitcnt vmcnt(6)
	ds_write2_b32 v42, v30, v31 offset1:1
	ds_write2_b32 v43, v32, v33 offset1:1
	s_waitcnt vmcnt(5)
	ds_write2_b32 v64, v34, v35 offset1:1
	ds_write2_b32 v65, v36, v37 offset1:1
	s_waitcnt vmcnt(4)
	ds_write2_b32 v66, v38, v39 offset1:1
	ds_write2_b32 v67, v40, v41 offset1:1
	s_waitcnt vmcnt(3)
	ds_write2_b32 v68, v48, v49 offset1:1
	ds_write2_b32 v69, v50, v51 offset1:1
	s_waitcnt vmcnt(2)
	ds_write2_b32 v70, v52, v53 offset1:1
	ds_write2_b32 v71, v54, v55 offset1:1
	s_waitcnt vmcnt(1)
	ds_write2_b32 v72, v56, v57 offset1:1
	ds_write2_b32 v73, v58, v59 offset1:1
	s_waitcnt vmcnt(0)
	ds_write2_b32 v74, v60, v61 offset1:1
	ds_write2_b32 v75, v62, v63 offset1:1
	s_waitcnt lgkmcnt(0)
	s_barrier
	ds_read2_b32 v[208:209], v22 offset1:65
	ds_read2_b32 v[210:211], v22 offset0:130 offset1:195
	v_add_u32_e32 v200, 0x400, v22
	ds_read2_b32 v[212:213], v200 offset0:4 offset1:69
	ds_read2_b32 v[214:215], v200 offset0:134 offset1:199
	ds_read2_b32 v[216:217], v23 offset1:65
	v_add_u32_e32 v201, 0x400, v23
	ds_read2_b32 v[218:219], v23 offset0:130 offset1:195
	ds_read2_b32 v[220:221], v201 offset0:4 offset1:69
	ds_read2_b32 v[222:223], v201 offset0:134 offset1:199
	s_waitcnt lgkmcnt(7)
	v_cvt_pk_bf16_f32 v26, v208, v209
	ds_read2_b32 v[224:225], v24 offset1:65
	s_waitcnt lgkmcnt(7)
	v_cvt_pk_bf16_f32 v27, v210, v211
	v_add_u32_e32 v202, 0x400, v24
	ds_read2_b32 v[226:227], v24 offset0:130 offset1:195
	s_waitcnt lgkmcnt(7)
	v_cvt_pk_bf16_f32 v28, v212, v213
	ds_read2_b32 v[228:229], v202 offset0:4 offset1:69
	v_or_b32_e32 v6, s85, v20
	v_lshlrev_b32_e32 v6, 12, v6
	v_lshl_add_u64 v[32:33], s[64:65], 0, v[6:7]
	v_lshl_add_u64 v[32:33], v[32:33], 0, s[26:27]
	s_waitcnt lgkmcnt(7)
	v_cvt_pk_bf16_f32 v29, v214, v215
	ds_read2_b32 v[230:231], v202 offset0:134 offset1:199
	v_lshl_add_u64 v[34:35], v[10:11], 1, v[32:33]
	global_store_dwordx4 v[34:35], v[26:29], off
	s_nop 1
	v_lshl_add_u64 v[34:35], v[12:13], 1, v[32:33]
	s_waitcnt lgkmcnt(7)
	v_cvt_pk_bf16_f32 v26, v216, v217
	ds_read2_b32 v[232:233], v25 offset1:65
	s_waitcnt lgkmcnt(7)
	v_cvt_pk_bf16_f32 v27, v218, v219
	v_add_u32_e32 v203, 0x400, v25
	ds_read2_b32 v[234:235], v25 offset0:130 offset1:195
	s_waitcnt lgkmcnt(7)
	v_cvt_pk_bf16_f32 v28, v220, v221
	ds_read2_b32 v[236:237], v203 offset0:4 offset1:69
	s_waitcnt lgkmcnt(7)
	v_cvt_pk_bf16_f32 v29, v222, v223
	ds_read2_b32 v[238:239], v203 offset0:134 offset1:199
	global_store_dwordx4 v[34:35], v[26:29], off
	s_nop 1
	v_lshl_add_u64 v[34:35], v[14:15], 1, v[32:33]
	s_waitcnt lgkmcnt(7)
	v_cvt_pk_bf16_f32 v26, v224, v225
	s_waitcnt lgkmcnt(6)
	v_cvt_pk_bf16_f32 v27, v226, v227
	s_waitcnt lgkmcnt(5)
	v_cvt_pk_bf16_f32 v28, v228, v229
	s_waitcnt lgkmcnt(4)
	v_cvt_pk_bf16_f32 v29, v230, v231
	global_store_dwordx4 v[34:35], v[26:29], off
	s_nop 1
	v_lshl_add_u64 v[32:33], v[16:17], 1, v[32:33]
	s_waitcnt lgkmcnt(3)
	v_cvt_pk_bf16_f32 v26, v232, v233
	s_waitcnt lgkmcnt(2)
	v_cvt_pk_bf16_f32 v27, v234, v235
	s_waitcnt lgkmcnt(1)
	v_cvt_pk_bf16_f32 v28, v236, v237
	s_waitcnt lgkmcnt(0)
	v_cvt_pk_bf16_f32 v29, v238, v239
	global_store_dwordx4 v[32:33], v[26:29], off
	s_nop 1
	s_barrier
	s_branch .LBB0_85

; __device__ __forceinline__ unsigned cvt_pk_bf16(float lo, float hi) { unsigned r; asm volatile("v_cvt_pk_bf16_f32 %0, %1, %2" : "=v"(r) : "v"(lo), "v"(hi)); return r; }
; __device__ __forceinline__ void cvt_matrix(const float* __restrict__ src, int K, int N, bf16_t* __restrict__ dst, int kind, int& base, float* lds_f, const int wv) {
;     ...
;         const int g_ = q_ * PER + (sl_ < 3 ? b_ + G * sl_ : 3 * G + b_ - 32), t = g_ - base;
;         if (t < 0 || t >= ntiles) continue;
;         const int kt = t / nnb, nb = t % nnb, k0 = kt * 256, n0 = nb * 64;
;         int drow0 = n0, perm = 0;
;         if (kind == 1) { if (n0 < DFF) drow0 = 256 * (n0 >> 7) + (n0 & 127); else { const int n1 = n0 - DFF; drow0 = 256 * (n1 >> 7) + 128 + (n1 & 127); } }
;         if (kind == 2) perm = (n0 % 192) == 128;
;         { const int c4 = tid & 15, kr = tid >> 4;
;           f32x4 v[8];
; #pragma unroll
;           for (int i = 0; i < 8; ++i) v[i] = __builtin_nontemporal_load((const f32x4*)(src + (size_t)(k0 + kr + 32 * i) * N + n0 + 4 * c4));
; #pragma unroll
;           for (int i = 0; i < 8; ++i) { float* l = lds_f + (kr + 32 * i) * 65 + 4 * c4; l[0] = v[i][0]; l[1] = v[i][1]; l[2] = v[i][2]; l[3] = v[i][3]; } }
;         __syncthreads();
; #pragma unroll
;         for (int j = 0; j < 4; ++j) { const int idx = tid + 512 * j, r = ((idx >> 6) & 3) * 16 + ((idx >> 2) & 15), kc = (idx >> 8) * 4 + (idx & 3);
;             const int sc = perm ? ((r & 1) ? 32 + (r >> 1) : (r >> 1)) : r;
;             const float* l = lds_f + (kc * 8) * 65 + sc;
;             u32x4 w; w.x = cvt_pk_bf16(l[0], l[65]); w.y = cvt_pk_bf16(l[2 * 65], l[3 * 65]); w.z = cvt_pk_bf16(l[4 * 65], l[5 * 65]); w.w = cvt_pk_bf16(l[6 * 65], l[7 * 65]);
;             *(u32x4*)(dst + (size_t)(drow0 + r) * K + k0 + kc * 8) = w; }
;         __syncthreads();
.LBB0_98:
	s_cmpk_gt_u32 s86, 0xff
	s_cbranch_scc1 .LBB0_97
	s_and_b32 s2, s88, 0x700
	s_and_b32 s90, s89, 0x7c0
	v_add_u32_e32 v26, s2, v18
	s_lshl_b32 s26, s90, 2
	v_ashrrev_i32_e32 v27, 31, v26
	v_lshl_add_u64 v[28:29], v[8:9], 0, s[26:27]
	v_lshlrev_b64 v[26:27], 13, v[26:27]
	v_lshl_add_u64 v[42:43], v[28:29], 0, v[26:27]
	v_add_co_u32_e32 v30, vcc, 0x40000, v42
	v_add_u32_e32 v6, v19, v21
	s_nop 0
	v_addc_co_u32_e32 v31, vcc, 0, v43, vcc
	v_add_co_u32_e32 v34, vcc, 0x80000, v42
	global_load_dwordx4 v[26:29], v[42:43], off nt
	s_nop 0
	global_load_dwordx4 v[30:33], v[30:31], off nt
	v_addc_co_u32_e32 v35, vcc, 0, v43, vcc
	v_add_co_u32_e32 v38, vcc, 0xc0000, v42
	v_add_u32_e32 v64, 0x4100, v6
	s_nop 0
	v_addc_co_u32_e32 v39, vcc, 0, v43, vcc
	v_add_co_u32_e32 v48, vcc, 0x100000, v42
	global_load_dwordx4 v[34:37], v[34:35], off nt
	s_nop 0
	global_load_dwordx4 v[38:41], v[38:39], off nt
	v_addc_co_u32_e32 v49, vcc, 0, v43, vcc
	v_add_co_u32_e32 v52, vcc, 0x140000, v42
	v_add_u32_e32 v65, 0x4108, v6
	s_nop 0
	v_addc_co_u32_e32 v53, vcc, 0, v43, vcc
	global_load_dwordx4 v[48:51], v[48:49], off nt
	s_nop 0
	global_load_dwordx4 v[52:55], v[52:53], off nt
	v_add_co_u32_e32 v56, vcc, 0x180000, v42
	v_add_u32_e32 v66, 0x6180, v6
	s_nop 0
	v_addc_co_u32_e32 v57, vcc, 0, v43, vcc
	global_load_dwordx4 v[56:59], v[56:57], off nt
	v_add_co_u32_e32 v42, vcc, 0x1c0000, v42
	v_add_u32_e32 v67, 0x6188, v6
	s_nop 0
	v_addc_co_u32_e32 v43, vcc, 0, v43, vcc
	global_load_dwordx4 v[60:63], v[42:43], off nt
	v_add_u32_e32 v42, 0x2080, v6
	v_add_u32_e32 v43, 0x2088, v6
	v_add_u32_e32 v68, 0x8200, v6
	v_add_u32_e32 v69, 0x8208, v6
	v_add_u32_e32 v70, 0xa280, v6
	v_add_u32_e32 v71, 0xa288, v6
	v_add_u32_e32 v72, 0xc300, v6
	v_add_u32_e32 v73, 0xc308, v6
	v_add_u32_e32 v74, 0xe380, v6
	v_add_u32_e32 v75, 0xe388, v6
	s_lshl_b32 s26, s2, 1
	s_waitcnt vmcnt(7)
	ds_write2_b32 v6, v26, v27 offset1:1
	ds_write2_b32 v6, v28, v29 offset0:2 offset1:3
	s_waitcnt vmcnt(6)
	ds_write2_b32 v42, v30, v31 offset1:1
	ds_write2_b32 v43, v32, v33 offset1:1
	s_waitcnt vmcnt(5)
	ds_write2_b32 v64, v34, v35 offset1:1
	ds_write2_b32 v65, v36, v37 offset1:1
	s_waitcnt vmcnt(4)
	ds_write2_b32 v66, v38, v39 offset1:1
	ds_write2_b32 v67, v40, v41 offset1:1
	s_waitcnt vmcnt(3)
	ds_write2_b32 v68, v48, v49 offset1:1
	ds_write2_b32 v69, v50, v51 offset1:1
	s_waitcnt vmcnt(2)
	ds_write2_b32 v70, v52, v53 offset1:1
	ds_write2_b32 v71, v54, v55 offset1:1
	s_waitcnt vmcnt(1)
	ds_write2_b32 v72, v56, v57 offset1:1
	ds_write2_b32 v73, v58, v59 offset1:1
	s_waitcnt vmcnt(0)
	ds_write2_b32 v74, v60, v61 offset1:1
	ds_write2_b32 v75, v62, v63 offset1:1
	s_waitcnt lgkmcnt(0)
	s_barrier
	ds_read2_b32 v[208:209], v22 offset1:65
	ds_read2_b32 v[210:211], v22 offset0:130 offset1:195
	v_add_u32_e32 v200, 0x400, v22
	ds_read2_b32 v[212:213], v200 offset0:4 offset1:69
	ds_read2_b32 v[214:215], v200 offset0:134 offset1:199
	ds_read2_b32 v[216:217], v23 offset1:65
	v_add_u32_e32 v201, 0x400, v23
	ds_read2_b32 v[218:219], v23 offset0:130 offset1:195
	ds_read2_b32 v[220:221], v201 offset0:4 offset1:69
	ds_read2_b32 v[222:223], v201 offset0:134 offset1:199
	s_waitcnt lgkmcnt(7)
	v_cvt_pk_bf16_f32 v26, v208, v209
	ds_read2_b32 v[224:225], v24 offset1:65
	s_waitcnt lgkmcnt(7)
	v_cvt_pk_bf16_f32 v27, v210, v211
	v_add_u32_e32 v202, 0x400, v24
	ds_read2_b32 v[226:227], v24 offset0:130 offset1:195
	s_waitcnt lgkmcnt(7)
	v_cvt_pk_bf16_f32 v28, v212, v213
	ds_read2_b32 v[228:229], v202 offset0:4 offset1:69
	v_or_b32_e32 v6, s90, v20
	v_lshlrev_b32_e32 v6, 12, v6
	v_lshl_add_u64 v[32:33], s[64:65], 0, v[6:7]
	v_lshl_add_u64 v[32:33], v[32:33], 0, s[26:27]
	s_waitcnt lgkmcnt(7)
	v_cvt_pk_bf16_f32 v29, v214, v215
	ds_read2_b32 v[230:231], v202 offset0:134 offset1:199
	v_lshl_add_u64 v[34:35], v[10:11], 1, v[32:33]
	global_store_dwordx4 v[34:35], v[26:29], off
	s_nop 1
	v_lshl_add_u64 v[34:35], v[12:13], 1, v[32:33]
	s_waitcnt lgkmcnt(7)
	v_cvt_pk_bf16_f32 v26, v216, v217
	ds_read2_b32 v[232:233], v25 offset1:65
	s_waitcnt lgkmcnt(7)
	v_cvt_pk_bf16_f32 v27, v218, v219
	v_add_u32_e32 v203, 0x400, v25
	ds_read2_b32 v[234:235], v25 offset0:130 offset1:195
	s_waitcnt lgkmcnt(7)
	v_cvt_pk_bf16_f32 v28, v220, v221
	ds_read2_b32 v[236:237], v203 offset0:4 offset1:69
	s_waitcnt lgkmcnt(7)
	v_cvt_pk_bf16_f32 v29, v222, v223
	ds_read2_b32 v[238:239], v203 offset0:134 offset1:199
	global_store_dwordx4 v[34:35], v[26:29], off
	s_nop 1
	v_lshl_add_u64 v[34:35], v[14:15], 1, v[32:33]
	s_waitcnt lgkmcnt(7)
	v_cvt_pk_bf16_f32 v26, v224, v225
	s_waitcnt lgkmcnt(6)
	v_cvt_pk_bf16_f32 v27, v226, v227
	s_waitcnt lgkmcnt(5)
	v_cvt_pk_bf16_f32 v28, v228, v229
	s_waitcnt lgkmcnt(4)
	v_cvt_pk_bf16_f32 v29, v230, v231
	global_store_dwordx4 v[34:35], v[26:29], off
	s_nop 1
	v_lshl_add_u64 v[32:33], v[16:17], 1, v[32:33]
	s_waitcnt lgkmcnt(3)
	v_cvt_pk_bf16_f32 v26, v232, v233
	s_waitcnt lgkmcnt(2)
	v_cvt_pk_bf16_f32 v27, v234, v235
	s_waitcnt lgkmcnt(1)
	v_cvt_pk_bf16_f32 v28, v236, v237
	s_waitcnt lgkmcnt(0)
	v_cvt_pk_bf16_f32 v29, v238, v239
	global_store_dwordx4 v[32:33], v[26:29], off
	s_nop 1
	s_barrier
	s_branch .LBB0_97
; __device__ __forceinline__ unsigned cvt_pk_bf16(float lo, float hi) { unsigned r; asm volatile("v_cvt_pk_bf16_f32 %0, %1, %2" : "=v"(r) : "v"(lo), "v"(hi)); return r; }
; __device__ __forceinline__ void cvt_matrix(const float* __restrict__ src, int K, int N, bf16_t* __restrict__ dst, int kind, int& base, float* lds_f, const int wv) {
;     ...
;         const int g_ = q_ * PER + (sl_ < 3 ? b_ + G * sl_ : 3 * G + b_ - 32), t = g_ - base;
;         if (t < 0 || t >= ntiles) continue;
;         const int kt = t / nnb, nb = t % nnb, k0 = kt * 256, n0 = nb * 64;
;         int drow0 = n0, perm = 0;
;         if (kind == 1) { if (n0 < DFF) drow0 = 256 * (n0 >> 7) + (n0 & 127); else { const int n1 = n0 - DFF; drow0 = 256 * (n1 >> 7) + 128 + (n1 & 127); } }
;         if (kind == 2) perm = (n0 % 192) == 128;
;         { const int c4 = tid & 15, kr = tid >> 4;
;           f32x4 v[8];
; #pragma unroll
;           for (int i = 0; i < 8; ++i) v[i] = __builtin_nontemporal_load((const f32x4*)(src + (size_t)(k0 + kr + 32 * i) * N + n0 + 4 * c4));
; #pragma unroll
;           for (int i = 0; i < 8; ++i) { float* l = lds_f + (kr + 32 * i) * 65 + 4 * c4; l[0] = v[i][0]; l[1] = v[i][1]; l[2] = v[i][2]; l[3] = v[i][3]; } }
;         __syncthreads();
; #pragma unroll
;         for (int j = 0; j < 4; ++j) { const int idx = tid + 512 * j, r = ((idx >> 6) & 3) * 16 + ((idx >> 2) & 15), kc = (idx >> 8) * 4 + (idx & 3);
;             const int sc = perm ? ((r & 1) ? 32 + (r >> 1) : (r >> 1)) : r;
;             const float* l = lds_f + (kc * 8) * 65 + sc;
;             u32x4 w; w.x = cvt_pk_bf16(l[0], l[65]); w.y = cvt_pk_bf16(l[2 * 65], l[3 * 65]); w.z = cvt_pk_bf16(l[4 * 65], l[5 * 65]); w.w = cvt_pk_bf16(l[6 * 65], l[7 * 65]);
;             *(u32x4*)(dst + (size_t)(drow0 + r) * K + k0 + kc * 8) = w; }
;         __syncthreads();
.LBB0_100:
	s_andn2_b64 vcc, exec, s[28:29]
	s_cbranch_vccnz .LBB0_95
	s_add_i32 s26, s77, s85
	s_cmpk_gt_u32 s26, 0xff
	s_cbranch_scc1 .LBB0_95
	s_lshl_b32 s2, s26, 3
	s_and_b32 s2, s2, 0x700
	s_lshl_b32 s26, s26, 6
	s_and_b32 s85, s26, 0x7c0
	v_add_u32_e32 v26, s2, v18
	s_lshl_b32 s26, s85, 2
	v_ashrrev_i32_e32 v27, 31, v26
	v_lshl_add_u64 v[28:29], v[8:9], 0, s[26:27]
	v_lshlrev_b64 v[26:27], 13, v[26:27]
	v_lshl_add_u64 v[42:43], v[28:29], 0, v[26:27]
	v_add_co_u32_e32 v30, vcc, 0x40000, v42
	v_add_u32_e32 v6, v19, v21
	s_nop 0
	v_addc_co_u32_e32 v31, vcc, 0, v43, vcc
	v_add_co_u32_e32 v34, vcc, 0x80000, v42
	global_load_dwordx4 v[26:29], v[42:43], off nt
	s_nop 0
	global_load_dwordx4 v[30:33], v[30:31], off nt
	v_addc_co_u32_e32 v35, vcc, 0, v43, vcc
	v_add_co_u32_e32 v38, vcc, 0xc0000, v42
	v_add_u32_e32 v64, 0x4100, v6
	s_nop 0
	v_addc_co_u32_e32 v39, vcc, 0, v43, vcc
	v_add_co_u32_e32 v48, vcc, 0x100000, v42
	global_load_dwordx4 v[34:37], v[34:35], off nt
	s_nop 0
	global_load_dwordx4 v[38:41], v[38:39], off nt
	v_addc_co_u32_e32 v49, vcc, 0, v43, vcc
	v_add_co_u32_e32 v52, vcc, 0x140000, v42
	v_add_u32_e32 v65, 0x4108, v6
	s_nop 0
	v_addc_co_u32_e32 v53, vcc, 0, v43, vcc
	global_load_dwordx4 v[48:51], v[48:49], off nt
	s_nop 0
	global_load_dwordx4 v[52:55], v[52:53], off nt
	v_add_co_u32_e32 v56, vcc, 0x180000, v42
	v_add_u32_e32 v66, 0x6180, v6
	s_nop 0
	v_addc_co_u32_e32 v57, vcc, 0, v43, vcc
	global_load_dwordx4 v[56:59], v[56:57], off nt
	v_add_co_u32_e32 v42, vcc, 0x1c0000, v42
	v_add_u32_e32 v67, 0x6188, v6
	s_nop 0
	v_addc_co_u32_e32 v43, vcc, 0, v43, vcc
	global_load_dwordx4 v[60:63], v[42:43], off nt
	v_add_u32_e32 v42, 0x2080, v6
	v_add_u32_e32 v43, 0x2088, v6
	v_add_u32_e32 v68, 0x8200, v6
	v_add_u32_e32 v69, 0x8208, v6
	v_add_u32_e32 v70, 0xa280, v6
	v_add_u32_e32 v71, 0xa288, v6
	v_add_u32_e32 v72, 0xc300, v6
	v_add_u32_e32 v73, 0xc308, v6
	v_add_u32_e32 v74, 0xe380, v6
	v_add_u32_e32 v75, 0xe388, v6
	s_lshl_b32 s26, s2, 1
	s_waitcnt vmcnt(7)
	ds_write2_b32 v6, v26, v27 offset1:1
	ds_write2_b32 v6, v28, v29 offset0:2 offset1:3
	s_waitcnt vmcnt(6)
	ds_write2_b32 v42, v30, v31 offset1:1
	ds_write2_b32 v43, v32, v33 offset1:1
	s_waitcnt vmcnt(5)
	ds_write2_b32 v64, v34, v35 offset1:1
	ds_write2_b32 v65, v36, v37 offset1:1
	s_waitcnt vmcnt(4)
	ds_write2_b32 v66, v38, v39 offset1:1
	ds_write2_b32 v67, v40, v41 offset1:1
	s_waitcnt vmcnt(3)
	ds_write2_b32 v68, v48, v49 offset1:1
	ds_write2_b32 v69, v50, v51 offset1:1
	s_waitcnt vmcnt(2)
	ds_write2_b32 v70, v52, v53 offset1:1
	ds_write2_b32 v71, v54, v55 offset1:1
	s_waitcnt vmcnt(1)
	ds_write2_b32 v72, v56, v57 offset1:1
	ds_write2_b32 v73, v58, v59 offset1:1
	s_waitcnt vmcnt(0)
	ds_write2_b32 v74, v60, v61 offset1:1
	ds_write2_b32 v75, v62, v63 offset1:1
	s_waitcnt lgkmcnt(0)
	s_barrier
	ds_read2_b32 v[208:209], v22 offset1:65
	ds_read2_b32 v[210:211], v22 offset0:130 offset1:195
	v_add_u32_e32 v200, 0x400, v22
	ds_read2_b32 v[212:213], v200 offset0:4 offset1:69
	ds_read2_b32 v[214:215], v200 offset0:134 offset1:199
	ds_read2_b32 v[216:217], v23 offset1:65
	v_add_u32_e32 v201, 0x400, v23
	ds_read2_b32 v[218:219], v23 offset0:130 offset1:195
	ds_read2_b32 v[220:221], v201 offset0:4 offset1:69
	ds_read2_b32 v[222:223], v201 offset0:134 offset1:199
	s_waitcnt lgkmcnt(7)
	v_cvt_pk_bf16_f32 v26, v208, v209
	ds_read2_b32 v[224:225], v24 offset1:65
	s_waitcnt lgkmcnt(7)
	v_cvt_pk_bf16_f32 v27, v210, v211
	v_add_u32_e32 v202, 0x400, v24
	ds_read2_b32 v[226:227], v24 offset0:130 offset1:195
	s_waitcnt lgkmcnt(7)
	v_cvt_pk_bf16_f32 v28, v212, v213
	ds_read2_b32 v[228:229], v202 offset0:4 offset1:69
	v_or_b32_e32 v6, s85, v20
	v_lshlrev_b32_e32 v6, 12, v6
	v_lshl_add_u64 v[32:33], s[64:65], 0, v[6:7]
	v_lshl_add_u64 v[32:33], v[32:33], 0, s[26:27]
	s_waitcnt lgkmcnt(7)
	v_cvt_pk_bf16_f32 v29, v214, v215
	ds_read2_b32 v[230:231], v202 offset0:134 offset1:199
	v_lshl_add_u64 v[34:35], v[10:11], 1, v[32:33]
	global_store_dwordx4 v[34:35], v[26:29], off
	s_nop 1
	v_lshl_add_u64 v[34:35], v[12:13], 1, v[32:33]
	s_waitcnt lgkmcnt(7)
	v_cvt_pk_bf16_f32 v26, v216, v217
	ds_read2_b32 v[232:233], v25 offset1:65
	s_waitcnt lgkmcnt(7)
	v_cvt_pk_bf16_f32 v27, v218, v219
	v_add_u32_e32 v203, 0x400, v25
	ds_read2_b32 v[234:235], v25 offset0:130 offset1:195
	s_waitcnt lgkmcnt(7)
	v_cvt_pk_bf16_f32 v28, v220, v221
	ds_read2_b32 v[236:237], v203 offset0:4 offset1:69
	s_waitcnt lgkmcnt(7)
	v_cvt_pk_bf16_f32 v29, v222, v223
	ds_read2_b32 v[238:239], v203 offset0:134 offset1:199
	global_store_dwordx4 v[34:35], v[26:29], off
	s_nop 1
	v_lshl_add_u64 v[34:35], v[14:15], 1, v[32:33]
	s_waitcnt lgkmcnt(7)
	v_cvt_pk_bf16_f32 v26, v224, v225
	s_waitcnt lgkmcnt(6)
	v_cvt_pk_bf16_f32 v27, v226, v227
	s_waitcnt lgkmcnt(5)
	v_cvt_pk_bf16_f32 v28, v228, v229
	s_waitcnt lgkmcnt(4)
	v_cvt_pk_bf16_f32 v29, v230, v231
	global_store_dwordx4 v[34:35], v[26:29], off
	s_nop 1
	v_lshl_add_u64 v[32:33], v[16:17], 1, v[32:33]
	s_waitcnt lgkmcnt(3)
	v_cvt_pk_bf16_f32 v26, v232, v233
	s_waitcnt lgkmcnt(2)
	v_cvt_pk_bf16_f32 v27, v234, v235
	s_waitcnt lgkmcnt(1)
	v_cvt_pk_bf16_f32 v28, v236, v237
	s_waitcnt lgkmcnt(0)
	v_cvt_pk_bf16_f32 v29, v238, v239
	global_store_dwordx4 v[32:33], v[26:29], off
	s_nop 1
	s_barrier
	s_branch .LBB0_95

; __device__ __forceinline__ unsigned cvt_pk_bf16(float lo, float hi) { unsigned r; asm volatile("v_cvt_pk_bf16_f32 %0, %1, %2" : "=v"(r) : "v"(lo), "v"(hi)); return r; }
; __device__ __forceinline__ void cvt_matrix(const float* __restrict__ src, int K, int N, bf16_t* __restrict__ dst, int kind, int& base, float* lds_f, const int wv) {
;     ...
;         const int g_ = q_ * PER + (sl_ < 3 ? b_ + G * sl_ : 3 * G + b_ - 32), t = g_ - base;
;         if (t < 0 || t >= ntiles) continue;
;         const int kt = t / nnb, nb = t % nnb, k0 = kt * 256, n0 = nb * 64;
;         int drow0 = n0, perm = 0;
;         if (kind == 1) { if (n0 < DFF) drow0 = 256 * (n0 >> 7) + (n0 & 127); else { const int n1 = n0 - DFF; drow0 = 256 * (n1 >> 7) + 128 + (n1 & 127); } }
;         if (kind == 2) perm = (n0 % 192) == 128;
;         { const int c4 = tid & 15, kr = tid >> 4;
;           f32x4 v[8];
; #pragma unroll
;           for (int i = 0; i < 8; ++i) v[i] = __builtin_nontemporal_load((const f32x4*)(src + (size_t)(k0 + kr + 32 * i) * N + n0 + 4 * c4));
; #pragma unroll
;           for (int i = 0; i < 8; ++i) { float* l = lds_f + (kr + 32 * i) * 65 + 4 * c4; l[0] = v[i][0]; l[1] = v[i][1]; l[2] = v[i][2]; l[3] = v[i][3]; } }
;         __syncthreads();
; #pragma unroll
;         for (int j = 0; j < 4; ++j) { const int idx = tid + 512 * j, r = ((idx >> 6) & 3) * 16 + ((idx >> 2) & 15), kc = (idx >> 8) * 4 + (idx & 3);
;             const int sc = perm ? ((r & 1) ? 32 + (r >> 1) : (r >> 1)) : r;
;             const float* l = lds_f + (kc * 8) * 65 + sc;
;             u32x4 w; w.x = cvt_pk_bf16(l[0], l[65]); w.y = cvt_pk_bf16(l[2 * 65], l[3 * 65]); w.z = cvt_pk_bf16(l[4 * 65], l[5 * 65]); w.w = cvt_pk_bf16(l[6 * 65], l[7 * 65]);
;             *(u32x4*)(dst + (size_t)(drow0 + r) * K + k0 + kc * 8) = w; }
;         __syncthreads();
.LBB0_108:
	s_cmp_gt_u32 s86, 23
	s_cbranch_scc1 .LBB0_107
	s_cmp_gt_u32 s86, 11
	s_cselect_b32 s2, 0x100, 0
	s_add_i32 s26, s87, 0xfffffd00
	s_cmp_lt_u32 s86, 12
	s_cselect_b32 s26, s87, s26
	v_add_u32_e32 v6, s2, v18
	v_lshl_add_u64 v[60:61], s[26:27], 2, v[8:9]
	v_add_u32_e32 v27, 32, v6
	v_mad_i64_i32 v[32:33], s[90:91], v27, s82, v[60:61]
	v_add_u32_e32 v27, 64, v6
	v_mad_i64_i32 v[36:37], s[90:91], v27, s82, v[60:61]
	v_add_u32_e32 v27, 0x60, v6
	v_mad_i64_i32 v[40:41], s[90:91], v27, s82, v[60:61]
	v_add_u32_e32 v27, 0x80, v6
	v_mad_i64_i32 v[48:49], s[90:91], v27, s82, v[60:61]
	v_add_u32_e32 v27, 0xa0, v6
	v_mad_i64_i32 v[28:29], s[90:91], v6, s82, v[60:61]
	v_mad_i64_i32 v[52:53], s[90:91], v27, s82, v[60:61]
	global_load_dwordx4 v[28:31], v[28:29], off nt
	s_nop 0
	global_load_dwordx4 v[32:35], v[32:33], off nt
	s_nop 0
	global_load_dwordx4 v[36:39], v[36:37], off nt
	s_nop 0
	global_load_dwordx4 v[40:43], v[40:41], off nt
	s_nop 0
	global_load_dwordx4 v[48:51], v[48:49], off nt
	s_nop 0
	global_load_dwordx4 v[52:55], v[52:53], off nt
	v_add_u32_e32 v27, 0xc0, v6
	v_mad_i64_i32 v[56:57], s[90:91], v27, s82, v[60:61]
	global_load_dwordx4 v[56:59], v[56:57], off nt
	v_add_u32_e32 v6, 0xe0, v6
	v_mad_i64_i32 v[60:61], s[90:91], v6, s82, v[60:61]
	global_load_dwordx4 v[60:63], v[60:61], off nt
	s_mul_i32 s89, s26, 0xaaaaaaab
	s_add_i32 s89, s89, 0xaaaaaa80
	v_alignbit_b32 v77, s89, s89, 6
	v_cmp_gt_u32_e32 vcc, s81, v77
	v_add_u32_e32 v6, v19, v21
	v_add_u32_e32 v27, 0x2080, v6
	v_cndmask_b32_e32 v77, v20, v22, vcc
	v_lshlrev_b32_e32 v77, 2, v77
	v_add_u32_e32 v78, v23, v77
	v_add_u32_e32 v64, 0x2088, v6
	v_add_u32_e32 v65, 0x4100, v6
	v_add_u32_e32 v66, 0x4108, v6
	v_add_u32_e32 v67, 0x6180, v6
	v_add_u32_e32 v68, 0x6188, v6
	v_add_u32_e32 v69, 0x8200, v6
	v_add_u32_e32 v70, 0x8208, v6
	v_add_u32_e32 v71, 0xa280, v6
	v_add_u32_e32 v72, 0xa288, v6
	v_add_u32_e32 v73, 0xc300, v6
	v_add_u32_e32 v74, 0xc308, v6
	v_add_u32_e32 v75, 0xe380, v6
	v_add_u32_e32 v76, 0xe388, v6
	s_waitcnt vmcnt(7)
	ds_write2_b32 v6, v28, v29 offset1:1
	ds_write2_b32 v6, v30, v31 offset0:2 offset1:3
	s_waitcnt vmcnt(6)
	ds_write2_b32 v27, v32, v33 offset1:1
	ds_write2_b32 v64, v34, v35 offset1:1
	s_waitcnt vmcnt(5)
	ds_write2_b32 v65, v36, v37 offset1:1
	ds_write2_b32 v66, v38, v39 offset1:1
	s_waitcnt vmcnt(4)
	ds_write2_b32 v67, v40, v41 offset1:1
	ds_write2_b32 v68, v42, v43 offset1:1
	s_waitcnt vmcnt(3)
	ds_write2_b32 v69, v48, v49 offset1:1
	ds_write2_b32 v70, v50, v51 offset1:1
	s_waitcnt vmcnt(2)
	ds_write2_b32 v71, v52, v53 offset1:1
	ds_write2_b32 v72, v54, v55 offset1:1
	s_waitcnt vmcnt(1)
	ds_write2_b32 v73, v56, v57 offset1:1
	ds_write2_b32 v74, v58, v59 offset1:1
	s_waitcnt vmcnt(0)
	ds_write2_b32 v75, v60, v61 offset1:1
	ds_write2_b32 v76, v62, v63 offset1:1
	s_waitcnt lgkmcnt(0)
	s_barrier
	ds_read2_b32 v[208:209], v78 offset1:65
	ds_read2_b32 v[210:211], v78 offset0:130 offset1:195
	v_add_u32_e32 v200, 0x400, v78
	ds_read2_b32 v[212:213], v200 offset0:4 offset1:69
	ds_read2_b32 v[214:215], v200 offset0:134 offset1:199
	v_add_u32_e32 v201, v24, v77
	ds_read2_b32 v[216:217], v201 offset1:65
	ds_read2_b32 v[218:219], v201 offset0:130 offset1:195
	v_add_u32_e32 v202, 0x400, v201
	ds_read2_b32 v[220:221], v202 offset0:4 offset1:69
	ds_read2_b32 v[222:223], v202 offset0:134 offset1:199
	s_waitcnt lgkmcnt(7)
	v_cvt_pk_bf16_f32 v28, v208, v209
	v_add_u32_e32 v203, v25, v77
	ds_read2_b32 v[224:225], v203 offset1:65
	s_waitcnt lgkmcnt(7)
	v_cvt_pk_bf16_f32 v29, v210, v211
	ds_read2_b32 v[226:227], v203 offset0:130 offset1:195
	s_waitcnt lgkmcnt(7)
	v_cvt_pk_bf16_f32 v30, v212, v213
	v_add_u32_e32 v204, 0x400, v203
	ds_read2_b32 v[228:229], v204 offset0:4 offset1:69
	v_or_b32_e32 v6, s26, v20
	v_lshlrev_b64 v[34:35], 10, v[6:7]
	s_lshl_b32 s26, s2, 1
	v_lshl_add_u64 v[34:35], s[64:65], 0, v[34:35]
	v_lshl_add_u64 v[34:35], v[34:35], 0, s[26:27]
	s_waitcnt lgkmcnt(7)
	v_cvt_pk_bf16_f32 v31, v214, v215
	ds_read2_b32 v[230:231], v204 offset0:134 offset1:199
	v_lshl_add_u64 v[36:37], v[10:11], 1, v[34:35]
	global_store_dwordx4 v[36:37], v[28:31], off
	s_nop 1
	v_lshl_add_u64 v[36:37], v[12:13], 1, v[34:35]
	s_waitcnt lgkmcnt(7)
	v_cvt_pk_bf16_f32 v28, v216, v217
	v_add_u32_e32 v205, v26, v77
	ds_read2_b32 v[232:233], v205 offset1:65
	s_waitcnt lgkmcnt(7)
	v_cvt_pk_bf16_f32 v29, v218, v219
	ds_read2_b32 v[234:235], v205 offset0:130 offset1:195
	s_waitcnt lgkmcnt(7)
	v_cvt_pk_bf16_f32 v30, v220, v221
	v_add_u32_e32 v206, 0x400, v205
	ds_read2_b32 v[236:237], v206 offset0:4 offset1:69
	s_waitcnt lgkmcnt(7)
	v_cvt_pk_bf16_f32 v31, v222, v223
	ds_read2_b32 v[238:239], v206 offset0:134 offset1:199
	global_store_dwordx4 v[36:37], v[28:31], off
	s_nop 1
	v_lshl_add_u64 v[36:37], v[14:15], 1, v[34:35]
	v_lshl_add_u64 v[34:35], v[16:17], 1, v[34:35]
	s_waitcnt lgkmcnt(7)
	v_cvt_pk_bf16_f32 v28, v224, v225
	s_waitcnt lgkmcnt(6)
	v_cvt_pk_bf16_f32 v29, v226, v227
	s_waitcnt lgkmcnt(5)
	v_cvt_pk_bf16_f32 v30, v228, v229
	s_waitcnt lgkmcnt(4)
	v_cvt_pk_bf16_f32 v31, v230, v231
	global_store_dwordx4 v[36:37], v[28:31], off
	s_nop 1
	s_nop 0
	s_waitcnt lgkmcnt(3)
	v_cvt_pk_bf16_f32 v28, v232, v233
	s_waitcnt lgkmcnt(2)
	v_cvt_pk_bf16_f32 v29, v234, v235
	s_waitcnt lgkmcnt(1)
	v_cvt_pk_bf16_f32 v30, v236, v237
	s_waitcnt lgkmcnt(0)
	v_cvt_pk_bf16_f32 v31, v238, v239
	global_store_dwordx4 v[34:35], v[28:31], off
	s_nop 1
	s_barrier
	s_branch .LBB0_107
; __device__ __forceinline__ unsigned cvt_pk_bf16(float lo, float hi) { unsigned r; asm volatile("v_cvt_pk_bf16_f32 %0, %1, %2" : "=v"(r) : "v"(lo), "v"(hi)); return r; }
; __device__ __forceinline__ void cvt_matrix(const float* __restrict__ src, int K, int N, bf16_t* __restrict__ dst, int kind, int& base, float* lds_f, const int wv) {
;     ...
;         const int g_ = q_ * PER + (sl_ < 3 ? b_ + G * sl_ : 3 * G + b_ - 32), t = g_ - base;
;         if (t < 0 || t >= ntiles) continue;
;         const int kt = t / nnb, nb = t % nnb, k0 = kt * 256, n0 = nb * 64;
;         int drow0 = n0, perm = 0;
;         if (kind == 1) { if (n0 < DFF) drow0 = 256 * (n0 >> 7) + (n0 & 127); else { const int n1 = n0 - DFF; drow0 = 256 * (n1 >> 7) + 128 + (n1 & 127); } }
;         if (kind == 2) perm = (n0 % 192) == 128;
;         { const int c4 = tid & 15, kr = tid >> 4;
;           f32x4 v[8];
; #pragma unroll
;           for (int i = 0; i < 8; ++i) v[i] = __builtin_nontemporal_load((const f32x4*)(src + (size_t)(k0 + kr + 32 * i) * N + n0 + 4 * c4));
; #pragma unroll
;           for (int i = 0; i < 8; ++i) { float* l = lds_f + (kr + 32 * i) * 65 + 4 * c4; l[0] = v[i][0]; l[1] = v[i][1]; l[2] = v[i][2]; l[3] = v[i][3]; } }
;         __syncthreads();
; #pragma unroll
;         for (int j = 0; j < 4; ++j) { const int idx = tid + 512 * j, r = ((idx >> 6) & 3) * 16 + ((idx >> 2) & 15), kc = (idx >> 8) * 4 + (idx & 3);
;             const int sc = perm ? ((r & 1) ? 32 + (r >> 1) : (r >> 1)) : r;
;             const float* l = lds_f + (kc * 8) * 65 + sc;
;             u32x4 w; w.x = cvt_pk_bf16(l[0], l[65]); w.y = cvt_pk_bf16(l[2 * 65], l[3 * 65]); w.z = cvt_pk_bf16(l[4 * 65], l[5 * 65]); w.w = cvt_pk_bf16(l[6 * 65], l[7 * 65]);
;             *(u32x4*)(dst + (size_t)(drow0 + r) * K + k0 + kc * 8) = w; }
;         __syncthreads();
.LBB0_110:
	s_andn2_b64 vcc, exec, s[28:29]
	s_cbranch_vccnz .LBB0_105
	s_add_i32 s26, s77, s85
	s_cmp_gt_u32 s26, 23
	s_cbranch_scc1 .LBB0_105
	s_cmp_gt_u32 s26, 11
	s_cselect_b32 s2, 0x100, 0
	s_lshl_b32 s85, s26, 6
	s_add_i32 s86, s85, 0xfffffd00
	s_cmp_lt_u32 s26, 12
	s_cselect_b32 s26, s85, s86
	v_add_u32_e32 v6, s2, v18
	v_lshl_add_u64 v[60:61], s[26:27], 2, v[8:9]
	v_add_u32_e32 v27, 32, v6
	v_mad_i64_i32 v[32:33], s[86:87], v27, s82, v[60:61]
	v_add_u32_e32 v27, 64, v6
	v_mad_i64_i32 v[36:37], s[86:87], v27, s82, v[60:61]
	v_add_u32_e32 v27, 0x60, v6
	v_mad_i64_i32 v[40:41], s[86:87], v27, s82, v[60:61]
	v_add_u32_e32 v27, 0x80, v6
	v_mad_i64_i32 v[48:49], s[86:87], v27, s82, v[60:61]
	v_add_u32_e32 v27, 0xa0, v6
	v_mad_i64_i32 v[28:29], s[86:87], v6, s82, v[60:61]
	v_mad_i64_i32 v[52:53], s[86:87], v27, s82, v[60:61]
	global_load_dwordx4 v[28:31], v[28:29], off nt
	s_nop 0
	global_load_dwordx4 v[32:35], v[32:33], off nt
	s_nop 0
	global_load_dwordx4 v[36:39], v[36:37], off nt
	s_nop 0
	global_load_dwordx4 v[40:43], v[40:41], off nt
	s_nop 0
	global_load_dwordx4 v[48:51], v[48:49], off nt
	s_nop 0
	global_load_dwordx4 v[52:55], v[52:53], off nt
	v_add_u32_e32 v27, 0xc0, v6
	v_mad_i64_i32 v[56:57], s[86:87], v27, s82, v[60:61]
	global_load_dwordx4 v[56:59], v[56:57], off nt
	v_add_u32_e32 v6, 0xe0, v6
	v_mad_i64_i32 v[60:61], s[86:87], v6, s82, v[60:61]
	global_load_dwordx4 v[60:63], v[60:61], off nt
	s_mul_i32 s85, s26, 0xaaaaaaab
	s_add_i32 s85, s85, 0xaaaaaa80
	v_alignbit_b32 v77, s85, s85, 6
	v_cmp_gt_u32_e32 vcc, s81, v77
	v_add_u32_e32 v6, v19, v21
	v_add_u32_e32 v27, 0x2080, v6
	v_cndmask_b32_e32 v77, v20, v22, vcc
	v_lshlrev_b32_e32 v77, 2, v77
	v_add_u32_e32 v78, v23, v77
	v_add_u32_e32 v64, 0x2088, v6
	v_add_u32_e32 v65, 0x4100, v6
	v_add_u32_e32 v66, 0x4108, v6
	v_add_u32_e32 v67, 0x6180, v6
	v_add_u32_e32 v68, 0x6188, v6
	v_add_u32_e32 v69, 0x8200, v6
	v_add_u32_e32 v70, 0x8208, v6
	v_add_u32_e32 v71, 0xa280, v6
	v_add_u32_e32 v72, 0xa288, v6
	v_add_u32_e32 v73, 0xc300, v6
	v_add_u32_e32 v74, 0xc308, v6
	v_add_u32_e32 v75, 0xe380, v6
	v_add_u32_e32 v76, 0xe388, v6
	s_waitcnt vmcnt(7)
	ds_write2_b32 v6, v28, v29 offset1:1
	ds_write2_b32 v6, v30, v31 offset0:2 offset1:3
	s_waitcnt vmcnt(6)
	ds_write2_b32 v27, v32, v33 offset1:1
	ds_write2_b32 v64, v34, v35 offset1:1
	s_waitcnt vmcnt(5)
	ds_write2_b32 v65, v36, v37 offset1:1
	ds_write2_b32 v66, v38, v39 offset1:1
	s_waitcnt vmcnt(4)
	ds_write2_b32 v67, v40, v41 offset1:1
	ds_write2_b32 v68, v42, v43 offset1:1
	s_waitcnt vmcnt(3)
	ds_write2_b32 v69, v48, v49 offset1:1
	ds_write2_b32 v70, v50, v51 offset1:1
	s_waitcnt vmcnt(2)
	ds_write2_b32 v71, v52, v53 offset1:1
	ds_write2_b32 v72, v54, v55 offset1:1
	s_waitcnt vmcnt(1)
	ds_write2_b32 v73, v56, v57 offset1:1
	ds_write2_b32 v74, v58, v59 offset1:1
	s_waitcnt vmcnt(0)
	ds_write2_b32 v75, v60, v61 offset1:1
	ds_write2_b32 v76, v62, v63 offset1:1
	s_waitcnt lgkmcnt(0)
	s_barrier
	ds_read2_b32 v[208:209], v78 offset1:65
	ds_read2_b32 v[210:211], v78 offset0:130 offset1:195
	v_add_u32_e32 v200, 0x400, v78
	ds_read2_b32 v[212:213], v200 offset0:4 offset1:69
	ds_read2_b32 v[214:215], v200 offset0:134 offset1:199
	v_add_u32_e32 v201, v24, v77
	ds_read2_b32 v[216:217], v201 offset1:65
	ds_read2_b32 v[218:219], v201 offset0:130 offset1:195
	v_add_u32_e32 v202, 0x400, v201
	ds_read2_b32 v[220:221], v202 offset0:4 offset1:69
	ds_read2_b32 v[222:223], v202 offset0:134 offset1:199
	s_waitcnt lgkmcnt(7)
	v_cvt_pk_bf16_f32 v28, v208, v209
	v_add_u32_e32 v203, v25, v77
	ds_read2_b32 v[224:225], v203 offset1:65
	s_waitcnt lgkmcnt(7)
	v_cvt_pk_bf16_f32 v29, v210, v211
	ds_read2_b32 v[226:227], v203 offset0:130 offset1:195
	s_waitcnt lgkmcnt(7)
	v_cvt_pk_bf16_f32 v30, v212, v213
	v_add_u32_e32 v204, 0x400, v203
	ds_read2_b32 v[228:229], v204 offset0:4 offset1:69
	v_or_b32_e32 v6, s26, v20
	v_lshlrev_b64 v[34:35], 10, v[6:7]
	s_lshl_b32 s26, s2, 1
	v_lshl_add_u64 v[34:35], s[64:65], 0, v[34:35]
	v_lshl_add_u64 v[34:35], v[34:35], 0, s[26:27]
	s_waitcnt lgkmcnt(7)
	v_cvt_pk_bf16_f32 v31, v214, v215
	ds_read2_b32 v[230:231], v204 offset0:134 offset1:199
	v_lshl_add_u64 v[36:37], v[10:11], 1, v[34:35]
	global_store_dwordx4 v[36:37], v[28:31], off
	s_nop 1
	v_lshl_add_u64 v[36:37], v[12:13], 1, v[34:35]
	s_waitcnt lgkmcnt(7)
	v_cvt_pk_bf16_f32 v28, v216, v217
	v_add_u32_e32 v205, v26, v77
	ds_read2_b32 v[232:233], v205 offset1:65
	s_waitcnt lgkmcnt(7)
	v_cvt_pk_bf16_f32 v29, v218, v219
	ds_read2_b32 v[234:235], v205 offset0:130 offset1:195
	s_waitcnt lgkmcnt(7)
	v_cvt_pk_bf16_f32 v30, v220, v221
	v_add_u32_e32 v206, 0x400, v205
	ds_read2_b32 v[236:237], v206 offset0:4 offset1:69
	s_waitcnt lgkmcnt(7)
	v_cvt_pk_bf16_f32 v31, v222, v223
	ds_read2_b32 v[238:239], v206 offset0:134 offset1:199
	global_store_dwordx4 v[36:37], v[28:31], off
	s_nop 1
	v_lshl_add_u64 v[36:37], v[14:15], 1, v[34:35]
	v_lshl_add_u64 v[34:35], v[16:17], 1, v[34:35]
	s_waitcnt lgkmcnt(7)
	v_cvt_pk_bf16_f32 v28, v224, v225
	s_waitcnt lgkmcnt(6)
	v_cvt_pk_bf16_f32 v29, v226, v227
	s_waitcnt lgkmcnt(5)
	v_cvt_pk_bf16_f32 v30, v228, v229
	s_waitcnt lgkmcnt(4)
	v_cvt_pk_bf16_f32 v31, v230, v231
	global_store_dwordx4 v[36:37], v[28:31], off
	s_nop 1
	s_nop 0
	s_waitcnt lgkmcnt(3)
	v_cvt_pk_bf16_f32 v28, v232, v233
	s_waitcnt lgkmcnt(2)
	v_cvt_pk_bf16_f32 v29, v234, v235
	s_waitcnt lgkmcnt(1)
	v_cvt_pk_bf16_f32 v30, v236, v237
	s_waitcnt lgkmcnt(0)
	v_cvt_pk_bf16_f32 v31, v238, v239
	global_store_dwordx4 v[34:35], v[28:31], off
	s_nop 1
	s_barrier
	s_branch .LBB0_105

; __device__ __forceinline__ unsigned cvt_pk_bf16(float lo, float hi) { unsigned r; asm volatile("v_cvt_pk_bf16_f32 %0, %1, %2" : "=v"(r) : "v"(lo), "v"(hi)); return r; }
; __device__ __forceinline__ void cvt_matrix(const float* __restrict__ src, int K, int N, bf16_t* __restrict__ dst, int kind, int& base, float* lds_f, const int wv) {
;     ...
;         const int g_ = q_ * PER + (sl_ < 3 ? b_ + G * sl_ : 3 * G + b_ - 32), t = g_ - base;
;         if (t < 0 || t >= ntiles) continue;
;         const int kt = t / nnb, nb = t % nnb, k0 = kt * 256, n0 = nb * 64;
;         int drow0 = n0, perm = 0;
;         if (kind == 1) { if (n0 < DFF) drow0 = 256 * (n0 >> 7) + (n0 & 127); else { const int n1 = n0 - DFF; drow0 = 256 * (n1 >> 7) + 128 + (n1 & 127); } }
;         if (kind == 2) perm = (n0 % 192) == 128;
;         { const int c4 = tid & 15, kr = tid >> 4;
;           f32x4 v[8];
; #pragma unroll
;           for (int i = 0; i < 8; ++i) v[i] = __builtin_nontemporal_load((const f32x4*)(src + (size_t)(k0 + kr + 32 * i) * N + n0 + 4 * c4));
; #pragma unroll
;           for (int i = 0; i < 8; ++i) { float* l = lds_f + (kr + 32 * i) * 65 + 4 * c4; l[0] = v[i][0]; l[1] = v[i][1]; l[2] = v[i][2]; l[3] = v[i][3]; } }
;         __syncthreads();
; #pragma unroll
;         for (int j = 0; j < 4; ++j) { const int idx = tid + 512 * j, r = ((idx >> 6) & 3) * 16 + ((idx >> 2) & 15), kc = (idx >> 8) * 4 + (idx & 3);
;             const int sc = perm ? ((r & 1) ? 32 + (r >> 1) : (r >> 1)) : r;
;             const float* l = lds_f + (kc * 8) * 65 + sc;
;             u32x4 w; w.x = cvt_pk_bf16(l[0], l[65]); w.y = cvt_pk_bf16(l[2 * 65], l[3 * 65]); w.z = cvt_pk_bf16(l[4 * 65], l[5 * 65]); w.w = cvt_pk_bf16(l[6 * 65], l[7 * 65]);
;             *(u32x4*)(dst + (size_t)(drow0 + r) * K + k0 + kc * 8) = w; }
;         __syncthreads();
.LBB0_116:
	s_add_i32 s86, s65, s85
	s_cmp_lt_u32 s86, 16
	s_cbranch_scc0 .LBB0_120
	s_lshl_b32 s26, s86, 6
	v_lshl_add_u64 v[42:43], s[26:27], 2, v[8:9]
	v_lshl_add_u64 v[48:49], v[42:43], 0, v[18:19]
	global_load_dwordx4 v[48:51], v[48:49], off nt
	v_lshl_add_u64 v[52:53], v[42:43], 0, v[20:21]
	global_load_dwordx4 v[52:55], v[52:53], off nt
	v_lshl_add_u64 v[56:57], v[42:43], 0, v[22:23]
	global_load_dwordx4 v[56:59], v[56:57], off nt
	v_lshl_add_u64 v[60:61], v[42:43], 0, v[24:25]
	global_load_dwordx4 v[60:63], v[60:61], off nt
	v_lshl_add_u64 v[64:65], v[42:43], 0, v[26:27]
	global_load_dwordx4 v[64:67], v[64:65], off nt
	v_lshl_add_u64 v[68:69], v[42:43], 0, v[28:29]
	global_load_dwordx4 v[68:71], v[68:69], off nt
	v_lshl_add_u64 v[72:73], v[42:43], 0, v[30:31]
	global_load_dwordx4 v[72:75], v[72:73], off nt
	v_lshl_add_u64 v[42:43], v[42:43], 0, v[32:33]
	global_load_dwordx4 v[76:79], v[42:43], off nt
	v_add_u32_e32 v6, v34, v36
	v_add_u32_e32 v42, 0x2088, v6
	v_add_u32_e32 v43, 0x4100, v6
	v_add_u32_e32 v41, 0x2080, v6
	v_add_u32_e32 v80, 0x4108, v6
	v_add_u32_e32 v81, 0x6180, v6
	v_add_u32_e32 v82, 0x6188, v6
	v_add_u32_e32 v83, 0x8200, v6
	v_add_u32_e32 v84, 0x8208, v6
	v_add_u32_e32 v85, 0xa280, v6
	v_add_u32_e32 v86, 0xa288, v6
	v_add_u32_e32 v87, 0xc300, v6
	v_add_u32_e32 v88, 0xc308, v6
	v_add_u32_e32 v89, 0xe380, v6
	v_add_u32_e32 v90, 0xe388, v6
	s_waitcnt vmcnt(7)
	ds_write2_b32 v6, v48, v49 offset1:1
	ds_write2_b32 v6, v50, v51 offset0:2 offset1:3
	s_waitcnt vmcnt(6)
	ds_write2_b32 v41, v52, v53 offset1:1
	ds_write2_b32 v42, v54, v55 offset1:1
	s_waitcnt vmcnt(5)
	ds_write2_b32 v43, v56, v57 offset1:1
	ds_write2_b32 v80, v58, v59 offset1:1
	s_waitcnt vmcnt(4)
	ds_write2_b32 v81, v60, v61 offset1:1
	ds_write2_b32 v82, v62, v63 offset1:1
	s_waitcnt vmcnt(3)
	ds_write2_b32 v83, v64, v65 offset1:1
	ds_write2_b32 v84, v66, v67 offset1:1
	s_waitcnt vmcnt(2)
	ds_write2_b32 v85, v68, v69 offset1:1
	ds_write2_b32 v86, v70, v71 offset1:1
	s_waitcnt vmcnt(1)
	ds_write2_b32 v87, v72, v73 offset1:1
	ds_write2_b32 v88, v74, v75 offset1:1
	s_waitcnt vmcnt(0)
	ds_write2_b32 v89, v76, v77 offset1:1
	ds_write2_b32 v90, v78, v79 offset1:1
	s_waitcnt lgkmcnt(0)
	s_barrier
	ds_read2_b32 v[208:209], v37 offset1:65
	ds_read2_b32 v[210:211], v37 offset0:130 offset1:195
	v_add_u32_e32 v200, 0x400, v37
	ds_read2_b32 v[212:213], v200 offset0:4 offset1:69
	ds_read2_b32 v[214:215], v200 offset0:134 offset1:199
	ds_read2_b32 v[216:217], v38 offset1:65
	v_add_u32_e32 v201, 0x400, v38
	ds_read2_b32 v[218:219], v38 offset0:130 offset1:195
	ds_read2_b32 v[220:221], v201 offset0:4 offset1:69
	ds_read2_b32 v[222:223], v201 offset0:134 offset1:199
	s_waitcnt lgkmcnt(7)
	v_cvt_pk_bf16_f32 v48, v208, v209
	ds_read2_b32 v[224:225], v39 offset1:65
	s_waitcnt lgkmcnt(7)
	v_cvt_pk_bf16_f32 v49, v210, v211
	v_add_u32_e32 v202, 0x400, v39
	ds_read2_b32 v[226:227], v39 offset0:130 offset1:195
	s_waitcnt lgkmcnt(7)
	v_cvt_pk_bf16_f32 v50, v212, v213
	ds_read2_b32 v[228:229], v202 offset0:4 offset1:69
	v_or_b32_e32 v6, s26, v35
	v_lshlrev_b32_e32 v6, 9, v6
	v_lshl_add_u64 v[52:53], s[62:63], 0, v[6:7]
	s_waitcnt lgkmcnt(7)
	v_cvt_pk_bf16_f32 v51, v214, v215
	ds_read2_b32 v[230:231], v202 offset0:134 offset1:199
	v_lshl_add_u64 v[54:55], v[10:11], 1, v[52:53]
	global_store_dwordx4 v[54:55], v[48:51], off
	s_nop 1
	v_lshl_add_u64 v[54:55], v[12:13], 1, v[52:53]
	s_waitcnt lgkmcnt(7)
	v_cvt_pk_bf16_f32 v48, v216, v217
	ds_read2_b32 v[232:233], v40 offset1:65
	s_waitcnt lgkmcnt(7)
	v_cvt_pk_bf16_f32 v49, v218, v219
	v_add_u32_e32 v203, 0x400, v40
	ds_read2_b32 v[234:235], v40 offset0:130 offset1:195
	s_waitcnt lgkmcnt(7)
	v_cvt_pk_bf16_f32 v50, v220, v221
	ds_read2_b32 v[236:237], v203 offset0:4 offset1:69
	s_waitcnt lgkmcnt(7)
	v_cvt_pk_bf16_f32 v51, v222, v223
	ds_read2_b32 v[238:239], v203 offset0:134 offset1:199
	global_store_dwordx4 v[54:55], v[48:51], off
	s_nop 1
	v_lshl_add_u64 v[54:55], v[14:15], 1, v[52:53]
	s_waitcnt lgkmcnt(7)
	v_cvt_pk_bf16_f32 v48, v224, v225
	s_waitcnt lgkmcnt(6)
	v_cvt_pk_bf16_f32 v49, v226, v227
	s_waitcnt lgkmcnt(5)
	v_cvt_pk_bf16_f32 v50, v228, v229
	s_waitcnt lgkmcnt(4)
	v_cvt_pk_bf16_f32 v51, v230, v231
	global_store_dwordx4 v[54:55], v[48:51], off
	s_nop 1
	v_lshl_add_u64 v[52:53], v[16:17], 1, v[52:53]
	s_waitcnt lgkmcnt(3)
	v_cvt_pk_bf16_f32 v48, v232, v233
	s_waitcnt lgkmcnt(2)
	v_cvt_pk_bf16_f32 v49, v234, v235
	s_waitcnt lgkmcnt(1)
	v_cvt_pk_bf16_f32 v50, v236, v237
	s_waitcnt lgkmcnt(0)
	v_cvt_pk_bf16_f32 v51, v238, v239
	global_store_dwordx4 v[52:53], v[48:51], off
	s_nop 1
	s_barrier
	s_add_i32 s86, s86, s30
	s_cmp_gt_u32 s86, 15
	s_cbranch_scc0 .LBB0_121

; __device__ __forceinline__ unsigned cvt_pk_bf16(float lo, float hi) { unsigned r; asm volatile("v_cvt_pk_bf16_f32 %0, %1, %2" : "=v"(r) : "v"(lo), "v"(hi)); return r; }
; __device__ __forceinline__ void cvt_matrix(const float* __restrict__ src, int K, int N, bf16_t* __restrict__ dst, int kind, int& base, float* lds_f, const int wv) {
;     ...
;         const int g_ = q_ * PER + (sl_ < 3 ? b_ + G * sl_ : 3 * G + b_ - 32), t = g_ - base;
;         if (t < 0 || t >= ntiles) continue;
;         const int kt = t / nnb, nb = t % nnb, k0 = kt * 256, n0 = nb * 64;
;         int drow0 = n0, perm = 0;
;         if (kind == 1) { if (n0 < DFF) drow0 = 256 * (n0 >> 7) + (n0 & 127); else { const int n1 = n0 - DFF; drow0 = 256 * (n1 >> 7) + 128 + (n1 & 127); } }
;         if (kind == 2) perm = (n0 % 192) == 128;
;         { const int c4 = tid & 15, kr = tid >> 4;
;           f32x4 v[8];
; #pragma unroll
;           for (int i = 0; i < 8; ++i) v[i] = __builtin_nontemporal_load((const f32x4*)(src + (size_t)(k0 + kr + 32 * i) * N + n0 + 4 * c4));
; #pragma unroll
;           for (int i = 0; i < 8; ++i) { float* l = lds_f + (kr + 32 * i) * 65 + 4 * c4; l[0] = v[i][0]; l[1] = v[i][1]; l[2] = v[i][2]; l[3] = v[i][3]; } }
;         __syncthreads();
; #pragma unroll
;         for (int j = 0; j < 4; ++j) { const int idx = tid + 512 * j, r = ((idx >> 6) & 3) * 16 + ((idx >> 2) & 15), kc = (idx >> 8) * 4 + (idx & 3);
;             const int sc = perm ? ((r & 1) ? 32 + (r >> 1) : (r >> 1)) : r;
;             const float* l = lds_f + (kc * 8) * 65 + sc;
;             u32x4 w; w.x = cvt_pk_bf16(l[0], l[65]); w.y = cvt_pk_bf16(l[2 * 65], l[3 * 65]); w.z = cvt_pk_bf16(l[4 * 65], l[5 * 65]); w.w = cvt_pk_bf16(l[6 * 65], l[7 * 65]);
;             *(u32x4*)(dst + (size_t)(drow0 + r) * K + k0 + kc * 8) = w; }
;         __syncthreads();
.LBB0_119:
	s_lshl_b32 s26, s86, 6
	v_lshl_add_u64 v[42:43], s[26:27], 2, v[8:9]
	v_lshl_add_u64 v[48:49], v[42:43], 0, v[18:19]
	global_load_dwordx4 v[48:51], v[48:49], off nt
	v_lshl_add_u64 v[52:53], v[42:43], 0, v[20:21]
	global_load_dwordx4 v[52:55], v[52:53], off nt
	v_lshl_add_u64 v[56:57], v[42:43], 0, v[22:23]
	global_load_dwordx4 v[56:59], v[56:57], off nt
	v_lshl_add_u64 v[60:61], v[42:43], 0, v[24:25]
	global_load_dwordx4 v[60:63], v[60:61], off nt
	v_lshl_add_u64 v[64:65], v[42:43], 0, v[26:27]
	global_load_dwordx4 v[64:67], v[64:65], off nt
	v_lshl_add_u64 v[68:69], v[42:43], 0, v[28:29]
	global_load_dwordx4 v[68:71], v[68:69], off nt
	v_lshl_add_u64 v[72:73], v[42:43], 0, v[30:31]
	global_load_dwordx4 v[72:75], v[72:73], off nt
	v_lshl_add_u64 v[42:43], v[42:43], 0, v[32:33]
	global_load_dwordx4 v[76:79], v[42:43], off nt
	v_add_u32_e32 v6, v34, v36
	v_add_u32_e32 v42, 0x2088, v6
	v_add_u32_e32 v43, 0x4100, v6
	v_add_u32_e32 v41, 0x2080, v6
	v_add_u32_e32 v80, 0x4108, v6
	v_add_u32_e32 v81, 0x6180, v6
	v_add_u32_e32 v82, 0x6188, v6
	v_add_u32_e32 v83, 0x8200, v6
	v_add_u32_e32 v84, 0x8208, v6
	v_add_u32_e32 v85, 0xa280, v6
	v_add_u32_e32 v86, 0xa288, v6
	v_add_u32_e32 v87, 0xc300, v6
	v_add_u32_e32 v88, 0xc308, v6
	v_add_u32_e32 v89, 0xe380, v6
	v_add_u32_e32 v90, 0xe388, v6
	s_waitcnt vmcnt(7)
	ds_write2_b32 v6, v48, v49 offset1:1
	ds_write2_b32 v6, v50, v51 offset0:2 offset1:3
	s_waitcnt vmcnt(6)
	ds_write2_b32 v41, v52, v53 offset1:1
	ds_write2_b32 v42, v54, v55 offset1:1
	s_waitcnt vmcnt(5)
	ds_write2_b32 v43, v56, v57 offset1:1
	ds_write2_b32 v80, v58, v59 offset1:1
	s_waitcnt vmcnt(4)
	ds_write2_b32 v81, v60, v61 offset1:1
	ds_write2_b32 v82, v62, v63 offset1:1
	s_waitcnt vmcnt(3)
	ds_write2_b32 v83, v64, v65 offset1:1
	ds_write2_b32 v84, v66, v67 offset1:1
	s_waitcnt vmcnt(2)
	ds_write2_b32 v85, v68, v69 offset1:1
	ds_write2_b32 v86, v70, v71 offset1:1
	s_waitcnt vmcnt(1)
	ds_write2_b32 v87, v72, v73 offset1:1
	ds_write2_b32 v88, v74, v75 offset1:1
	s_waitcnt vmcnt(0)
	ds_write2_b32 v89, v76, v77 offset1:1
	ds_write2_b32 v90, v78, v79 offset1:1
	s_waitcnt lgkmcnt(0)
	s_barrier
	ds_read2_b32 v[208:209], v37 offset1:65
	ds_read2_b32 v[210:211], v37 offset0:130 offset1:195
	v_add_u32_e32 v200, 0x400, v37
	ds_read2_b32 v[212:213], v200 offset0:4 offset1:69
	ds_read2_b32 v[214:215], v200 offset0:134 offset1:199
	ds_read2_b32 v[216:217], v38 offset1:65
	v_add_u32_e32 v201, 0x400, v38
	ds_read2_b32 v[218:219], v38 offset0:130 offset1:195
	ds_read2_b32 v[220:221], v201 offset0:4 offset1:69
	ds_read2_b32 v[222:223], v201 offset0:134 offset1:199
	s_waitcnt lgkmcnt(7)
	v_cvt_pk_bf16_f32 v48, v208, v209
	ds_read2_b32 v[224:225], v39 offset1:65
	s_waitcnt lgkmcnt(7)
	v_cvt_pk_bf16_f32 v49, v210, v211
	v_add_u32_e32 v202, 0x400, v39
	ds_read2_b32 v[226:227], v39 offset0:130 offset1:195
	s_waitcnt lgkmcnt(7)
	v_cvt_pk_bf16_f32 v50, v212, v213
	ds_read2_b32 v[228:229], v202 offset0:4 offset1:69
	v_or_b32_e32 v6, s26, v35
	v_lshlrev_b32_e32 v6, 9, v6
	v_lshl_add_u64 v[52:53], s[62:63], 0, v[6:7]
	s_waitcnt lgkmcnt(7)
	v_cvt_pk_bf16_f32 v51, v214, v215
	ds_read2_b32 v[230:231], v202 offset0:134 offset1:199
	v_lshl_add_u64 v[54:55], v[10:11], 1, v[52:53]
	global_store_dwordx4 v[54:55], v[48:51], off
	s_nop 1
	v_lshl_add_u64 v[54:55], v[12:13], 1, v[52:53]
	s_waitcnt lgkmcnt(7)
	v_cvt_pk_bf16_f32 v48, v216, v217
	ds_read2_b32 v[232:233], v40 offset1:65
	s_waitcnt lgkmcnt(7)
	v_cvt_pk_bf16_f32 v49, v218, v219
	v_add_u32_e32 v203, 0x400, v40
	ds_read2_b32 v[234:235], v40 offset0:130 offset1:195
	s_waitcnt lgkmcnt(7)
	v_cvt_pk_bf16_f32 v50, v220, v221
	ds_read2_b32 v[236:237], v203 offset0:4 offset1:69
	s_waitcnt lgkmcnt(7)
	v_cvt_pk_bf16_f32 v51, v222, v223
	ds_read2_b32 v[238:239], v203 offset0:134 offset1:199
	global_store_dwordx4 v[54:55], v[48:51], off
	s_nop 1
	v_lshl_add_u64 v[54:55], v[14:15], 1, v[52:53]
	s_waitcnt lgkmcnt(7)
	v_cvt_pk_bf16_f32 v48, v224, v225
	s_waitcnt lgkmcnt(6)
	v_cvt_pk_bf16_f32 v49, v226, v227
	s_waitcnt lgkmcnt(5)
	v_cvt_pk_bf16_f32 v50, v228, v229
	s_waitcnt lgkmcnt(4)
	v_cvt_pk_bf16_f32 v51, v230, v231
	global_store_dwordx4 v[54:55], v[48:51], off
	s_nop 1
	v_lshl_add_u64 v[52:53], v[16:17], 1, v[52:53]
	s_waitcnt lgkmcnt(3)
	v_cvt_pk_bf16_f32 v48, v232, v233
	s_waitcnt lgkmcnt(2)
	v_cvt_pk_bf16_f32 v49, v234, v235
	s_waitcnt lgkmcnt(1)
	v_cvt_pk_bf16_f32 v50, v236, v237
	s_waitcnt lgkmcnt(0)
	v_cvt_pk_bf16_f32 v51, v238, v239
	global_store_dwordx4 v[52:53], v[48:51], off
	s_nop 1
	s_barrier
	s_and_b64 vcc, exec, s[28:29]
	s_cbranch_vccz .LBB0_115
	s_branch .LBB0_123

; __device__ __forceinline__ unsigned cvt_pk_bf16(float lo, float hi) { unsigned r; asm volatile("v_cvt_pk_bf16_f32 %0, %1, %2" : "=v"(r) : "v"(lo), "v"(hi)); return r; }
; __device__ __forceinline__ void cvt_matrix(const float* __restrict__ src, int K, int N, bf16_t* __restrict__ dst, int kind, int& base, float* lds_f, const int wv) {
;     ...
;         const int g_ = q_ * PER + (sl_ < 3 ? b_ + G * sl_ : 3 * G + b_ - 32), t = g_ - base;
;         if (t < 0 || t >= ntiles) continue;
;         const int kt = t / nnb, nb = t % nnb, k0 = kt * 256, n0 = nb * 64;
;         int drow0 = n0, perm = 0;
;         if (kind == 1) { if (n0 < DFF) drow0 = 256 * (n0 >> 7) + (n0 & 127); else { const int n1 = n0 - DFF; drow0 = 256 * (n1 >> 7) + 128 + (n1 & 127); } }
;         if (kind == 2) perm = (n0 % 192) == 128;
;         { const int c4 = tid & 15, kr = tid >> 4;
;           f32x4 v[8];
; #pragma unroll
;           for (int i = 0; i < 8; ++i) v[i] = __builtin_nontemporal_load((const f32x4*)(src + (size_t)(k0 + kr + 32 * i) * N + n0 + 4 * c4));
; #pragma unroll
;           for (int i = 0; i < 8; ++i) { float* l = lds_f + (kr + 32 * i) * 65 + 4 * c4; l[0] = v[i][0]; l[1] = v[i][1]; l[2] = v[i][2]; l[3] = v[i][3]; } }
;         __syncthreads();
; #pragma unroll
;         for (int j = 0; j < 4; ++j) { const int idx = tid + 512 * j, r = ((idx >> 6) & 3) * 16 + ((idx >> 2) & 15), kc = (idx >> 8) * 4 + (idx & 3);
;             const int sc = perm ? ((r & 1) ? 32 + (r >> 1) : (r >> 1)) : r;
;             const float* l = lds_f + (kc * 8) * 65 + sc;
;             u32x4 w; w.x = cvt_pk_bf16(l[0], l[65]); w.y = cvt_pk_bf16(l[2 * 65], l[3 * 65]); w.z = cvt_pk_bf16(l[4 * 65], l[5 * 65]); w.w = cvt_pk_bf16(l[6 * 65], l[7 * 65]);
;             *(u32x4*)(dst + (size_t)(drow0 + r) * K + k0 + kc * 8) = w; }
;         __syncthreads();
.LBB0_121:
	s_lshl_b32 s26, s86, 6
	v_lshl_add_u64 v[42:43], s[26:27], 2, v[8:9]
	v_lshl_add_u64 v[48:49], v[42:43], 0, v[18:19]
	global_load_dwordx4 v[48:51], v[48:49], off nt
	v_lshl_add_u64 v[52:53], v[42:43], 0, v[20:21]
	global_load_dwordx4 v[52:55], v[52:53], off nt
	v_lshl_add_u64 v[56:57], v[42:43], 0, v[22:23]
	global_load_dwordx4 v[56:59], v[56:57], off nt
	v_lshl_add_u64 v[60:61], v[42:43], 0, v[24:25]
	global_load_dwordx4 v[60:63], v[60:61], off nt
	v_lshl_add_u64 v[64:65], v[42:43], 0, v[26:27]
	global_load_dwordx4 v[64:67], v[64:65], off nt
	v_lshl_add_u64 v[68:69], v[42:43], 0, v[28:29]
	global_load_dwordx4 v[68:71], v[68:69], off nt
	v_lshl_add_u64 v[72:73], v[42:43], 0, v[30:31]
	global_load_dwordx4 v[72:75], v[72:73], off nt
	v_lshl_add_u64 v[42:43], v[42:43], 0, v[32:33]
	global_load_dwordx4 v[76:79], v[42:43], off nt
	v_add_u32_e32 v6, v34, v36
	v_add_u32_e32 v42, 0x2088, v6
	v_add_u32_e32 v43, 0x4100, v6
	v_add_u32_e32 v41, 0x2080, v6
	v_add_u32_e32 v80, 0x4108, v6
	v_add_u32_e32 v81, 0x6180, v6
	v_add_u32_e32 v82, 0x6188, v6
	v_add_u32_e32 v83, 0x8200, v6
	v_add_u32_e32 v84, 0x8208, v6
	v_add_u32_e32 v85, 0xa280, v6
	v_add_u32_e32 v86, 0xa288, v6
	v_add_u32_e32 v87, 0xc300, v6
	v_add_u32_e32 v88, 0xc308, v6
	v_add_u32_e32 v89, 0xe380, v6
	v_add_u32_e32 v90, 0xe388, v6
	s_waitcnt vmcnt(7)
	ds_write2_b32 v6, v48, v49 offset1:1
	ds_write2_b32 v6, v50, v51 offset0:2 offset1:3
	s_waitcnt vmcnt(6)
	ds_write2_b32 v41, v52, v53 offset1:1
	ds_write2_b32 v42, v54, v55 offset1:1
	s_waitcnt vmcnt(5)
	ds_write2_b32 v43, v56, v57 offset1:1
	ds_write2_b32 v80, v58, v59 offset1:1
	s_waitcnt vmcnt(4)
	ds_write2_b32 v81, v60, v61 offset1:1
	ds_write2_b32 v82, v62, v63 offset1:1
	s_waitcnt vmcnt(3)
	ds_write2_b32 v83, v64, v65 offset1:1
	ds_write2_b32 v84, v66, v67 offset1:1
	s_waitcnt vmcnt(2)
	ds_write2_b32 v85, v68, v69 offset1:1
	ds_write2_b32 v86, v70, v71 offset1:1
	s_waitcnt vmcnt(1)
	ds_write2_b32 v87, v72, v73 offset1:1
	ds_write2_b32 v88, v74, v75 offset1:1
	s_waitcnt vmcnt(0)
	ds_write2_b32 v89, v76, v77 offset1:1
	ds_write2_b32 v90, v78, v79 offset1:1
	s_waitcnt lgkmcnt(0)
	s_barrier
	ds_read2_b32 v[208:209], v37 offset1:65
	ds_read2_b32 v[210:211], v37 offset0:130 offset1:195
	v_add_u32_e32 v200, 0x400, v37
	ds_read2_b32 v[212:213], v200 offset0:4 offset1:69
	ds_read2_b32 v[214:215], v200 offset0:134 offset1:199
	ds_read2_b32 v[216:217], v38 offset1:65
	v_add_u32_e32 v201, 0x400, v38
	ds_read2_b32 v[218:219], v38 offset0:130 offset1:195
	ds_read2_b32 v[220:221], v201 offset0:4 offset1:69
	ds_read2_b32 v[222:223], v201 offset0:134 offset1:199
	s_waitcnt lgkmcnt(7)
	v_cvt_pk_bf16_f32 v48, v208, v209
	ds_read2_b32 v[224:225], v39 offset1:65
	s_waitcnt lgkmcnt(7)
	v_cvt_pk_bf16_f32 v49, v210, v211
	v_add_u32_e32 v202, 0x400, v39
	ds_read2_b32 v[226:227], v39 offset0:130 offset1:195
	s_waitcnt lgkmcnt(7)
	v_cvt_pk_bf16_f32 v50, v212, v213
	ds_read2_b32 v[228:229], v202 offset0:4 offset1:69
	v_or_b32_e32 v6, s26, v35
	v_lshlrev_b32_e32 v6, 9, v6
	v_lshl_add_u64 v[52:53], s[62:63], 0, v[6:7]
	s_waitcnt lgkmcnt(7)
	v_cvt_pk_bf16_f32 v51, v214, v215
	ds_read2_b32 v[230:231], v202 offset0:134 offset1:199
	v_lshl_add_u64 v[54:55], v[10:11], 1, v[52:53]
	global_store_dwordx4 v[54:55], v[48:51], off
	s_nop 1
	v_lshl_add_u64 v[54:55], v[12:13], 1, v[52:53]
	s_waitcnt lgkmcnt(7)
	v_cvt_pk_bf16_f32 v48, v216, v217
	ds_read2_b32 v[232:233], v40 offset1:65
	s_waitcnt lgkmcnt(7)
	v_cvt_pk_bf16_f32 v49, v218, v219
	v_add_u32_e32 v203, 0x400, v40
	ds_read2_b32 v[234:235], v40 offset0:130 offset1:195
	s_waitcnt lgkmcnt(7)
	v_cvt_pk_bf16_f32 v50, v220, v221
	ds_read2_b32 v[236:237], v203 offset0:4 offset1:69
	s_waitcnt lgkmcnt(7)
	v_cvt_pk_bf16_f32 v51, v222, v223
	ds_read2_b32 v[238:239], v203 offset0:134 offset1:199
	global_store_dwordx4 v[54:55], v[48:51], off
	s_nop 1
	v_lshl_add_u64 v[54:55], v[14:15], 1, v[52:53]
	s_waitcnt lgkmcnt(7)
	v_cvt_pk_bf16_f32 v48, v224, v225
	s_waitcnt lgkmcnt(6)
	v_cvt_pk_bf16_f32 v49, v226, v227
	s_waitcnt lgkmcnt(5)
	v_cvt_pk_bf16_f32 v50, v228, v229
	s_waitcnt lgkmcnt(4)
	v_cvt_pk_bf16_f32 v51, v230, v231
	global_store_dwordx4 v[54:55], v[48:51], off
	s_nop 1
	v_lshl_add_u64 v[52:53], v[16:17], 1, v[52:53]
	s_waitcnt lgkmcnt(3)
	v_cvt_pk_bf16_f32 v48, v232, v233
	s_waitcnt lgkmcnt(2)
	v_cvt_pk_bf16_f32 v49, v234, v235
	s_waitcnt lgkmcnt(1)
	v_cvt_pk_bf16_f32 v50, v236, v237
	s_waitcnt lgkmcnt(0)
	v_cvt_pk_bf16_f32 v51, v238, v239
	global_store_dwordx4 v[52:53], v[48:51], off
	s_nop 1
	s_barrier
	s_add_i32 s86, s86, s30
	s_cmp_gt_u32 s86, 15
	s_cbranch_scc0 .LBB0_119

; __device__ __forceinline__ unsigned cvt_pk_bf16(float lo, float hi) { unsigned r; asm volatile("v_cvt_pk_bf16_f32 %0, %1, %2" : "=v"(r) : "v"(lo), "v"(hi)); return r; }
; __device__ __forceinline__ void cvt_matrix(const float* __restrict__ src, int K, int N, bf16_t* __restrict__ dst, int kind, int& base, float* lds_f, const int wv) {
;     ...
;         const int g_ = q_ * PER + (sl_ < 3 ? b_ + G * sl_ : 3 * G + b_ - 32), t = g_ - base;
;         if (t < 0 || t >= ntiles) continue;
;         const int kt = t / nnb, nb = t % nnb, k0 = kt * 256, n0 = nb * 64;
;         int drow0 = n0, perm = 0;
;         if (kind == 1) { if (n0 < DFF) drow0 = 256 * (n0 >> 7) + (n0 & 127); else { const int n1 = n0 - DFF; drow0 = 256 * (n1 >> 7) + 128 + (n1 & 127); } }
;         if (kind == 2) perm = (n0 % 192) == 128;
;         { const int c4 = tid & 15, kr = tid >> 4;
;           f32x4 v[8];
; #pragma unroll
;           for (int i = 0; i < 8; ++i) v[i] = __builtin_nontemporal_load((const f32x4*)(src + (size_t)(k0 + kr + 32 * i) * N + n0 + 4 * c4));
; #pragma unroll
;           for (int i = 0; i < 8; ++i) { float* l = lds_f + (kr + 32 * i) * 65 + 4 * c4; l[0] = v[i][0]; l[1] = v[i][1]; l[2] = v[i][2]; l[3] = v[i][3]; } }
;         __syncthreads();
; #pragma unroll
;         for (int j = 0; j < 4; ++j) { const int idx = tid + 512 * j, r = ((idx >> 6) & 3) * 16 + ((idx >> 2) & 15), kc = (idx >> 8) * 4 + (idx & 3);
;             const int sc = perm ? ((r & 1) ? 32 + (r >> 1) : (r >> 1)) : r;
;             const float* l = lds_f + (kc * 8) * 65 + sc;
;             u32x4 w; w.x = cvt_pk_bf16(l[0], l[65]); w.y = cvt_pk_bf16(l[2 * 65], l[3 * 65]); w.z = cvt_pk_bf16(l[4 * 65], l[5 * 65]); w.w = cvt_pk_bf16(l[6 * 65], l[7 * 65]);
;             *(u32x4*)(dst + (size_t)(drow0 + r) * K + k0 + kc * 8) = w; }
;         __syncthreads();
.LBB0_123:
	s_add_i32 s26, s66, s85
	s_cmp_gt_u32 s26, 15
	s_cbranch_scc1 .LBB0_115
	s_lshl_b32 s26, s26, 6
	v_lshl_add_u64 v[42:43], s[26:27], 2, v[8:9]
	v_lshl_add_u64 v[48:49], v[42:43], 0, v[18:19]
	global_load_dwordx4 v[48:51], v[48:49], off nt
	v_lshl_add_u64 v[52:53], v[42:43], 0, v[20:21]
	global_load_dwordx4 v[52:55], v[52:53], off nt
	v_lshl_add_u64 v[56:57], v[42:43], 0, v[22:23]
	global_load_dwordx4 v[56:59], v[56:57], off nt
	v_lshl_add_u64 v[60:61], v[42:43], 0, v[24:25]
	global_load_dwordx4 v[60:63], v[60:61], off nt
	v_lshl_add_u64 v[64:65], v[42:43], 0, v[26:27]
	global_load_dwordx4 v[64:67], v[64:65], off nt
	v_lshl_add_u64 v[68:69], v[42:43], 0, v[28:29]
	global_load_dwordx4 v[68:71], v[68:69], off nt
	v_lshl_add_u64 v[72:73], v[42:43], 0, v[30:31]
	global_load_dwordx4 v[72:75], v[72:73], off nt
	v_lshl_add_u64 v[42:43], v[42:43], 0, v[32:33]
	global_load_dwordx4 v[76:79], v[42:43], off nt
	v_add_u32_e32 v6, v34, v36
	v_add_u32_e32 v42, 0x2088, v6
	v_add_u32_e32 v43, 0x4100, v6
	v_add_u32_e32 v41, 0x2080, v6
	v_add_u32_e32 v80, 0x4108, v6
	v_add_u32_e32 v81, 0x6180, v6
	v_add_u32_e32 v82, 0x6188, v6
	v_add_u32_e32 v83, 0x8200, v6
	v_add_u32_e32 v84, 0x8208, v6
	v_add_u32_e32 v85, 0xa280, v6
	v_add_u32_e32 v86, 0xa288, v6
	v_add_u32_e32 v87, 0xc300, v6
	v_add_u32_e32 v88, 0xc308, v6
	v_add_u32_e32 v89, 0xe380, v6
	v_add_u32_e32 v90, 0xe388, v6
	s_waitcnt vmcnt(7)
	ds_write2_b32 v6, v48, v49 offset1:1
	ds_write2_b32 v6, v50, v51 offset0:2 offset1:3
	s_waitcnt vmcnt(6)
	ds_write2_b32 v41, v52, v53 offset1:1
	ds_write2_b32 v42, v54, v55 offset1:1
	s_waitcnt vmcnt(5)
	ds_write2_b32 v43, v56, v57 offset1:1
	ds_write2_b32 v80, v58, v59 offset1:1
	s_waitcnt vmcnt(4)
	ds_write2_b32 v81, v60, v61 offset1:1
	ds_write2_b32 v82, v62, v63 offset1:1
	s_waitcnt vmcnt(3)
	ds_write2_b32 v83, v64, v65 offset1:1
	ds_write2_b32 v84, v66, v67 offset1:1
	s_waitcnt vmcnt(2)
	ds_write2_b32 v85, v68, v69 offset1:1
	ds_write2_b32 v86, v70, v71 offset1:1
	s_waitcnt vmcnt(1)
	ds_write2_b32 v87, v72, v73 offset1:1
	ds_write2_b32 v88, v74, v75 offset1:1
	s_waitcnt vmcnt(0)
	ds_write2_b32 v89, v76, v77 offset1:1
	ds_write2_b32 v90, v78, v79 offset1:1
	s_waitcnt lgkmcnt(0)
	s_barrier
	ds_read2_b32 v[208:209], v37 offset1:65
	ds_read2_b32 v[210:211], v37 offset0:130 offset1:195
	v_add_u32_e32 v200, 0x400, v37
	ds_read2_b32 v[212:213], v200 offset0:4 offset1:69
	ds_read2_b32 v[214:215], v200 offset0:134 offset1:199
	ds_read2_b32 v[216:217], v38 offset1:65
	v_add_u32_e32 v201, 0x400, v38
	ds_read2_b32 v[218:219], v38 offset0:130 offset1:195
	ds_read2_b32 v[220:221], v201 offset0:4 offset1:69
	ds_read2_b32 v[222:223], v201 offset0:134 offset1:199
	s_waitcnt lgkmcnt(7)
	v_cvt_pk_bf16_f32 v48, v208, v209
	ds_read2_b32 v[224:225], v39 offset1:65
	s_waitcnt lgkmcnt(7)
	v_cvt_pk_bf16_f32 v49, v210, v211
	v_add_u32_e32 v202, 0x400, v39
	ds_read2_b32 v[226:227], v39 offset0:130 offset1:195
	s_waitcnt lgkmcnt(7)
	v_cvt_pk_bf16_f32 v50, v212, v213
	ds_read2_b32 v[228:229], v202 offset0:4 offset1:69
	v_or_b32_e32 v6, s26, v35
	v_lshlrev_b32_e32 v6, 9, v6
	v_lshl_add_u64 v[52:53], s[62:63], 0, v[6:7]
	s_waitcnt lgkmcnt(7)
	v_cvt_pk_bf16_f32 v51, v214, v215
	ds_read2_b32 v[230:231], v202 offset0:134 offset1:199
	v_lshl_add_u64 v[54:55], v[10:11], 1, v[52:53]
	global_store_dwordx4 v[54:55], v[48:51], off
	s_nop 1
	v_lshl_add_u64 v[54:55], v[12:13], 1, v[52:53]
	s_waitcnt lgkmcnt(7)
	v_cvt_pk_bf16_f32 v48, v216, v217
	ds_read2_b32 v[232:233], v40 offset1:65
	s_waitcnt lgkmcnt(7)
	v_cvt_pk_bf16_f32 v49, v218, v219
	v_add_u32_e32 v203, 0x400, v40
	ds_read2_b32 v[234:235], v40 offset0:130 offset1:195
	s_waitcnt lgkmcnt(7)
	v_cvt_pk_bf16_f32 v50, v220, v221
	ds_read2_b32 v[236:237], v203 offset0:4 offset1:69
	s_waitcnt lgkmcnt(7)
	v_cvt_pk_bf16_f32 v51, v222, v223
	ds_read2_b32 v[238:239], v203 offset0:134 offset1:199
	global_store_dwordx4 v[54:55], v[48:51], off
	s_nop 1
	v_lshl_add_u64 v[54:55], v[14:15], 1, v[52:53]
	s_waitcnt lgkmcnt(7)
	v_cvt_pk_bf16_f32 v48, v224, v225
	s_waitcnt lgkmcnt(6)
	v_cvt_pk_bf16_f32 v49, v226, v227
	s_waitcnt lgkmcnt(5)
	v_cvt_pk_bf16_f32 v50, v228, v229
	s_waitcnt lgkmcnt(4)
	v_cvt_pk_bf16_f32 v51, v230, v231
	global_store_dwordx4 v[54:55], v[48:51], off
	s_nop 1
	v_lshl_add_u64 v[52:53], v[16:17], 1, v[52:53]
	s_waitcnt lgkmcnt(3)
	v_cvt_pk_bf16_f32 v48, v232, v233
	s_waitcnt lgkmcnt(2)
	v_cvt_pk_bf16_f32 v49, v234, v235
	s_waitcnt lgkmcnt(1)
	v_cvt_pk_bf16_f32 v50, v236, v237
	s_waitcnt lgkmcnt(0)
	v_cvt_pk_bf16_f32 v51, v238, v239
	global_store_dwordx4 v[52:53], v[48:51], off
	s_nop 1
	s_barrier
	s_branch .LBB0_115
